# attention epilogues: v_rcp_f32-based f32 division instead of the div_scale/fmas/fixup chains; row-sum shuffles by DPP/permlane16_swap; global loads with counted vmcnt; prologue table loads deferred
# speedup vs baseline: 1.0212x; 1.0199x over previous
; template <int MODE>
; __device__ __forceinline__ void attn_unit(const Tensors& T0, int ureq, int b, int hh, int qblk, LAS3 char* shm, const bool dummy = false) {
;     ...
;   { const float* gt = T.gtab + (MODE ? (16 + hh) : hh * 4) * TABW; for (int i = tid; i < (MODE ? 1 : 4) * TABW; i += 512) tab[i] = gt[i]; }
;   float cbL = 0.f, cbR = 0.f, lam = 0.f, sinkv = 0.f;
;   if (MODE) { cbL = T.gtab[(16 + hh) * TABW]; cbR = T.gtab[(16 + hh) * TABW + TABW - 1]; lam = T.lamp[0]; } else { sinkv = T.sink[hh * 4 + sub] * LOG2E; }
;   bf16x8 qr[4];
; #pragma unroll
;   for (int d0 = 0; d0 < 4; ++d0) qr[d0] = *reinterpret_cast<const bf16x8*>(&Qw[(long)r32 * PQ + d0 * 16 + hi * 8]);
;   asm volatile("s_waitcnt vmcnt(0)" ::: "memory");
;   const int drow = 8 * wid + (lane >> 3);
;   const bf16_t* ksrc = Kh + (long)drow * PK + (((lane & 7) ^ ((drow >> 1) & 7)) * 8);
;   const bf16_t* vsrc = Vh + (long)drow * PK + ((((lane >> 2) & 1) ^ ((lane >> 4) & 1)) * 32) + (lane & 3) * 8;
;   const unsigned dwv = lds0 + wid * 1024;
;     ...
;   int t_lo = 0, t_hi = S / 64;
;   if (!MODE) { t_lo = (Q0 >= 128 ? Q0 - 128 : 0) / 64; const int e = Q0 + 64 + 128; t_hi = (e < S ? e : S) / 64; }
;   const int NT = t_hi - t_lo;
;   const int grp = wid >> 2;
;   lds_cptr kp[4];
; #pragma unroll
;   for (int d0 = 0; d0 < 4; ++d0) kp[d0] = (lds_cptr)shm + (MODE ? sub * OFF_K2 : 0) + r32 * 128 + (((2 * d0 + hi) ^ ((r32 >> 1) & 7)) << 4);
;   const int vrow = 4 * hi + ((lane & 15) >> 2), vsw = (lane >> 3) & 1;
;   const lds_cptr vpe = (lds_cptr)shm + OFF_V + vrow * 128 + vsw * 64 + ((lane >> 4) & 1) * 32 + (lane & 3) * 8;
;   const lds_cptr vpo = (lds_cptr)shm + OFF_V + vrow * 128 + (vsw ^ 1) * 64 + ((lane >> 4) & 1) * 32 + (lane & 3) * 8;
;   float mhat, l_reg, curcb; bool first; f32x16 o[ND]; f32x16 negm; u32x4 pw[4];
;     ...
;   bf16x8 vA[ND], vB[ND];
;   mhat = MODE ? 0.f : sinkv; l_reg = (!MODE && hi == 0) ? 1.f : 0.f; curcb = 0.f; first = MODE ? true : false;
; #pragma unroll
;   for (int d = 0; d < ND; ++d) o[d] = f32x16{};
; #pragma unroll
;   for (int r = 0; r < 16; ++r) negm[r] = -mhat;
; #pragma unroll
;   for (int j = 0; j < 4; ++j) pw[j] = (u32x4){0u, 0u, 0u, 0u};
;   if (!(ATT_ABL == 2 && dummy)) { ATT_DMA(t_lo, 0); ATT_DMA(t_lo + 1, SLOTB); }
;   ATT_BAR_V(true);
;   if (grp == 1) { if (NT > 2 && !(ATT_ABL == 2 && dummy)) ATT_DMA(t_lo + 2, 2 * SLOTB); ATT_BAR_L(); }
.LBB0_87:
	v_mov_b32_e32 v112, v181
	s_mov_b64 s[4:5], s[24:25]
	s_mov_b64 s[78:79], s[16:17]
	s_mov_b64 s[6:7], s[26:27]
	s_mov_b64 s[50:51], s[20:21]
	s_movk_i32 s18, 0x240
	s_mov_b64 s[74:75], s[22:23]
	s_mov_b64 s[4:5], s[34:35]
	s_mov_b64 s[6:7], s[64:65]
	s_mov_b64 s[48:49], s[52:53]
	v_readfirstlane_b32 s91, v112
	v_cmp_gt_i32_e32 vcc, s18, v112
	s_and_saveexec_b64 s[74:75], vcc
	s_cbranch_execz .LBB0_90
	s_and_b32 s18, s11, 7
	s_mulk_i32 s18, 0x900
	s_add_u32 s76, s6, s18
	v_ashrrev_i32_e32 v113, 31, v112
	s_addc_u32 s77, s7, 0
	v_lshl_add_u64 v[16:17], v[112:113], 2, s[76:77]
	s_mov_b64 s[76:77], 0x9000
	v_add_u32_e32 v18, 0xfffffe00, v112
	v_lshl_add_u32 v19, v112, 2, s57
	v_lshl_add_u64 v[16:17], v[16:17], 0, s[76:77]
	global_load_dword v250, v[16:17], off
	v_mov_b32_e32 v252, v19
	v_cmp_gt_i32_e32 vcc, 64, v181
	s_and_b64 exec, exec, vcc
	s_cbranch_execz .LBB0_90
	global_load_dword v251, v[16:17], off offset:2048
.LBB0_90:
	s_or_b64 exec, exec, s[74:75]
	s_and_b32 s95, s11, 7
	s_ashr_i32 s11, s10, 31
	s_ashr_i32 s92, s91, 6
	s_lshl_b64 s[74:75], s[10:11], 13
	s_add_u32 s18, s74, 0x8000
	s_addc_u32 s76, s75, 0
	s_lshl_b64 s[10:11], s[10:11], 12
	s_and_b64 s[74:75], s[8:9], exec
	s_cselect_b32 s11, s11, s76
	s_cselect_b32 s80, s10, s18
	s_and_b32 s90, s92, 3
	s_lshl_b32 s96, s19, 7
	s_lshl_b32 s97, s90, 5
	s_ashr_i32 s10, s91, 8
	s_or_b32 s18, s97, s96
	s_add_u32 s74, s80, s18
	s_addc_u32 s75, s11, 0
	s_mul_i32 s76, s75, 0x1800
	s_mul_hi_u32 s77, s74, 0x1800
	s_add_i32 s77, s77, s76
	s_mul_i32 s76, s74, 0x1800
	s_add_u32 s76, s78, s76
	s_addc_u32 s77, s79, s77
	s_lshl_b32 s93, s95, 8
	s_add_u32 s81, s76, s93
	s_addc_u32 s82, s77, 0
	s_lshl_b32 s76, s10, 6
	s_ashr_i32 s77, s76, 31
	s_lshl_b64 s[76:77], s[76:77], 1
	s_add_u32 s76, s81, s76
	s_mulk_i32 s11, 0x1800
	s_mul_hi_u32 s81, s80, 0x1800
	s_addc_u32 s77, s82, s77
	s_add_i32 s94, s81, s11
	s_mul_i32 s98, s80, 0x1800
	s_add_u32 s11, s78, s98
	s_addc_u32 s81, s79, s94
	s_add_u32 s80, s11, s93
	s_addc_u32 s81, s81, 0
	s_add_u32 s82, s80, 0x1000
	s_addc_u32 s83, s81, 0
	s_mul_i32 s11, s95, 0x900
	s_add_u32 s6, s6, s11
	s_addc_u32 s7, s7, 0
	v_mov_b32_e32 v16, s6
	v_mov_b32_e32 v17, s7
	v_add_co_u32_e32 v16, vcc, s85, v16
	v_and_b32_e32 v186, 31, v112
	s_nop 0
	v_addc_co_u32_e32 v17, vcc, 0, v17, vcc
	global_load_dword v191, v[16:17], off
	global_load_dword v192, v[16:17], off offset:2300
	v_mov_b64_e32 v[16:17], s[4:5]
	global_load_dword v187, v[16:17], off
	v_mul_u32_u24_e32 v16, 0xc00, v186
	v_bfe_u32 v188, v112, 5, 1
	v_lshlrev_b32_e32 v16, 1, v16
	v_lshl_or_b32 v174, v188, 4, v16
	v_lshl_add_u64 v[16:17], s[76:77], 0, v[174:175]
	global_load_dwordx4 v[128:131], v[16:17], off
	global_load_dwordx4 v[132:135], v[16:17], off offset:32
	global_load_dwordx4 v[136:139], v[16:17], off offset:64
	global_load_dwordx4 v[140:143], v[16:17], off offset:96
	s_lshl_b32 s99, s92, 3
	v_bfe_u32 v113, v112, 3, 3
	v_or_b32_e32 v20, s99, v113
	v_lshrrev_b32_e32 v18, 1, v20
	v_xor_b32_e32 v127, v18, v112
	v_lshlrev_b32_e32 v18, 4, v127
	v_and_b32_e32 v174, 0x70, v18
	v_lshrrev_b32_e32 v146, 2, v112
	v_lshrrev_b32_e32 v145, 4, v112
	v_lshlrev_b32_e32 v18, 3, v112
	v_mov_b64_e32 v[16:17], s[80:81]
	v_xor_b32_e32 v126, v146, v145
	v_and_b32_e32 v144, 24, v18
	v_mov_b64_e32 v[18:19], s[82:83]
	v_mad_i64_i32 v[16:17], s[4:5], v20, s84, v[16:17]
	v_mad_i64_i32 v[18:19], s[4:5], v20, s84, v[18:19]
	v_lshlrev_b32_e32 v20, 6, v126
	v_lshl_add_u64 v[16:17], v[16:17], 0, v[174:175]
	s_lshl_b32 s92, s92, 10
	v_and_b32_e32 v174, 64, v20
	v_lshl_add_u64 v[114:115], v[16:17], 0, s[54:55]
	s_add_i32 s92, s92, 0
	v_lshl_add_u64 v[18:19], v[18:19], 0, v[174:175]
	v_lshlrev_b32_e32 v174, 1, v144
	s_mov_b32 s4, m0
	s_mov_b32 m0, s92
	s_nop 0
	global_load_lds_dwordx4 v[114:115], off
	s_mov_b32 m0, s4
	v_lshl_add_u64 v[116:117], v[18:19], 0, v[174:175]
	v_lshl_add_u64 v[18:19], v[16:17], 0, s[66:67]
	s_add_i32 s4, s92, 0x2000
	s_mov_b32 s5, m0
	s_mov_b32 m0, s4
	s_nop 0
	global_load_lds_dwordx4 v[18:19], off
	s_mov_b32 m0, s5
	s_add_i32 s4, s92, 0x4000
	s_mov_b32 s5, m0
	s_mov_b32 m0, s4
	s_nop 0
	global_load_lds_dwordx4 v[116:117], off
	s_mov_b32 m0, s5
	s_mov_b64 s[4:5], 0x80
	v_lshl_add_u64 v[18:19], v[116:117], 0, s[4:5]
	s_add_i32 s4, s92, 0x6000
	s_mov_b32 s5, m0
	s_mov_b32 m0, s4
	s_nop 0
	global_load_lds_dwordx4 v[18:19], off
	s_mov_b32 m0, s5
	s_mov_b64 s[4:5], 0x60800
	v_lshl_add_u64 v[18:19], v[16:17], 0, s[4:5]
	s_add_i32 s4, s92, 0x8000
	s_mov_b32 s5, m0
	s_mov_b32 m0, s4
	s_nop 0
	global_load_lds_dwordx4 v[18:19], off
	s_mov_b32 m0, s5
	s_mov_b64 s[4:5], 0x60880
	v_lshl_add_u64 v[16:17], v[16:17], 0, s[4:5]
	s_add_i32 s4, s92, 0xa000
	s_mov_b32 s5, m0
	s_mov_b32 m0, s4
	s_nop 0
	global_load_lds_dwordx4 v[16:17], off
	s_mov_b32 m0, s5
	v_lshl_add_u64 v[16:17], v[116:117], 0, s[68:69]
	s_add_i32 s4, s92, 0xc000
	s_mov_b32 s5, m0
	s_mov_b32 m0, s4
	s_nop 0
	global_load_lds_dwordx4 v[16:17], off
	s_mov_b32 m0, s5
	s_mov_b64 s[4:5], 0x60080
	v_lshl_add_u64 v[16:17], v[116:117], 0, s[4:5]
	s_add_i32 s4, s92, 0xe000
	s_mov_b32 s5, m0
	s_mov_b32 m0, s4
	s_nop 0
	global_load_lds_dwordx4 v[16:17], off
	s_mov_b32 m0, s5
	s_waitcnt vmcnt(15)
	ds_write_b32 v252, v250
	v_cmp_gt_i32_e32 vcc, 64, v181
	s_and_saveexec_b64 s[100:101], vcc
	ds_write_b32 v252, v251 offset:2048
	s_or_b64 exec, exec, s[100:101]
	s_waitcnt vmcnt(4) lgkmcnt(0)
	s_barrier
	s_cmp_eq_u32 s10, 1
	s_cselect_b64 s[80:81], -1, 0
	s_and_b64 vcc, exec, s[80:81]
	v_lshl_add_u64 v[124:125], v[114:115], 0, s[70:71]
	v_lshl_add_u64 v[122:123], v[114:115], 0, s[72:73]
	v_lshl_add_u64 v[120:121], v[116:117], 0, s[70:71]
	v_lshl_add_u64 v[118:119], v[116:117], 0, s[72:73]
	s_cbranch_vccz .LBB0_92
	s_add_i32 s4, s92, 0x10000
	s_mov_b32 s5, m0
	s_mov_b32 m0, s4
	s_nop 0
	global_load_lds_dwordx4 v[124:125], off
	s_mov_b32 m0, s5
	s_add_i32 s4, s92, 0x12000
	s_mov_b32 s5, m0
	s_mov_b32 m0, s4
	s_nop 0
	global_load_lds_dwordx4 v[122:123], off
	s_mov_b32 m0, s5
	s_add_i32 s4, s92, 0x14000
	s_mov_b32 s5, m0
	s_mov_b32 m0, s4
	s_nop 0
	global_load_lds_dwordx4 v[120:121], off
	s_mov_b32 m0, s5
	s_add_i32 s4, s92, 0x16000
	s_mov_b32 s5, m0
	s_mov_b32 m0, s4
	s_nop 0
	global_load_lds_dwordx4 v[118:119], off
	s_mov_b32 m0, s5
	s_waitcnt lgkmcnt(0)
	s_barrier

; #define LAS3 __attribute__((address_space(3)))
; __device__ __forceinline__ int crow(int r, int hi) { return (r & 3) + 8 * (r >> 2) + 4 * hi; }
; template <int MODE>
; __device__ __forceinline__ void attn_unit(const Tensors& T0, int ureq, int b, int hh, int qblk, LAS3 char* shm, const bool dummy = false) {
;     ...
;   float rli[16];
; #pragma unroll
;   for (int r = 0; r < 16; ++r) rli[r] = 1.0f / wsf[32 + crow(r, hi)];
;   if (MODE) {
;     bf16_t* const gpb = T.G + (size_t)(rowbase + q0w) * 2048 + 1024 + hh * 128 + r32;
;     bf16_t gv[2][16];
;     if (sub == 0 && !dummy) {
; #pragma unroll
;       for (int r = 0; r < 16; ++r) gv[0][r] = gpb[(size_t)crow(r, hi) * 2048]; }
;     asm volatile("s_waitcnt lgkmcnt(0)\n\ts_barrier" ::: "memory");
;     LAS3 float* X = (LAS3 float*)shm + rg * 4096;
;     if (sub == 1) {
; #pragma unroll
;       for (int d = 0; d < ND; ++d)
; #pragma unroll
;         for (int r = 0; r < 16; ++r) X[(d * 16 + r) * 64 + lane] = o[d][r] * rli[r] * lam;
.LBB0_140:
	s_waitcnt lgkmcnt(3)
	s_waitcnt lgkmcnt(0)
	s_barrier
	v_rcp_f32_e32 v110, v92
	s_nop 0
	v_rcp_f32_e32 v111, v93
	s_nop 0
	v_rcp_f32_e32 v112, v94
	s_nop 0
	s_waitcnt lgkmcnt(2)
	v_rcp_f32_e32 v113, v95
	s_nop 0
	v_rcp_f32_e32 v114, v88
	s_nop 0
	v_rcp_f32_e32 v115, v89
	s_nop 0
	v_rcp_f32_e32 v116, v90
	s_nop 0
	s_waitcnt lgkmcnt(1)
	v_rcp_f32_e32 v120, v91
	s_nop 0
	v_rcp_f32_e32 v134, v84
	s_nop 0
	v_rcp_f32_e32 v136, v85
	s_nop 0
	v_rcp_f32_e32 v137, v86
	s_nop 0
	s_waitcnt lgkmcnt(0)
	v_rcp_f32_e32 v138, v87
	s_nop 0
	v_rcp_f32_e32 v139, v80
	s_nop 0
	v_rcp_f32_e32 v141, v81
	s_nop 0
	v_rcp_f32_e32 v143, v82
	s_nop 0
	s_lshl_b32 s6, s90, 14
	s_add_i32 s6, s6, 0
	v_rcp_f32_e32 v147, v83
	s_nop 0
	s_and_b64 vcc, exec, s[10:11]
	v_lshl_add_u32 v140, v189, 2, s6
	s_cbranch_vccnz .LBB0_142
	v_mul_f32_e32 v80, v48, v110
	v_mul_f32_e32 v81, v49, v111
	v_mul_f32_e32 v80, v187, v80
	v_mul_f32_e32 v81, v187, v81
	ds_write2st64_b32 v140, v80, v81 offset1:1
	v_mul_f32_e32 v80, v50, v112
	v_mul_f32_e32 v81, v51, v113
	v_mul_f32_e32 v80, v187, v80
	v_mul_f32_e32 v81, v187, v81
	ds_write2st64_b32 v140, v80, v81 offset0:2 offset1:3
	v_mul_f32_e32 v80, v52, v114
	v_mul_f32_e32 v81, v53, v115
	v_mul_f32_e32 v80, v187, v80
	v_mul_f32_e32 v81, v187, v81
	ds_write2st64_b32 v140, v80, v81 offset0:4 offset1:5
	v_mul_f32_e32 v80, v54, v116
	v_mul_f32_e32 v81, v55, v120
	v_mul_f32_e32 v80, v187, v80
	v_mul_f32_e32 v81, v187, v81
	ds_write2st64_b32 v140, v80, v81 offset0:6 offset1:7
	v_mul_f32_e32 v80, v56, v134
	v_mul_f32_e32 v81, v57, v136
	v_mul_f32_e32 v80, v187, v80
	v_mul_f32_e32 v81, v187, v81
	ds_write2st64_b32 v140, v80, v81 offset0:8 offset1:9
	v_mul_f32_e32 v80, v58, v137
	v_mul_f32_e32 v81, v59, v138
	v_mul_f32_e32 v80, v187, v80
	v_mul_f32_e32 v81, v187, v81
	ds_write2st64_b32 v140, v80, v81 offset0:10 offset1:11
	v_mul_f32_e32 v80, v60, v139
	v_mul_f32_e32 v81, v61, v141
	v_mul_f32_e32 v80, v187, v80
	v_mul_f32_e32 v81, v187, v81
	ds_write2st64_b32 v140, v80, v81 offset0:12 offset1:13
	v_mul_f32_e32 v80, v62, v143
	v_mul_f32_e32 v81, v63, v147
	v_mul_f32_e32 v80, v187, v80
	v_mul_f32_e32 v81, v187, v81
	ds_write2st64_b32 v140, v80, v81 offset0:14 offset1:15
	v_mul_f32_e32 v80, v64, v110
	v_mul_f32_e32 v81, v65, v111
	v_mul_f32_e32 v80, v187, v80
	v_mul_f32_e32 v81, v187, v81
	ds_write2st64_b32 v140, v80, v81 offset0:16 offset1:17
	v_mul_f32_e32 v80, v66, v112
	v_mul_f32_e32 v81, v67, v113
	v_mul_f32_e32 v80, v187, v80
	v_mul_f32_e32 v81, v187, v81
	ds_write2st64_b32 v140, v80, v81 offset0:18 offset1:19
	v_mul_f32_e32 v80, v68, v114
	v_mul_f32_e32 v81, v69, v115
	v_mul_f32_e32 v80, v187, v80
	v_mul_f32_e32 v81, v187, v81
	ds_write2st64_b32 v140, v80, v81 offset0:20 offset1:21
	v_mul_f32_e32 v80, v70, v116
	v_mul_f32_e32 v81, v71, v120
	v_mul_f32_e32 v80, v187, v80
	v_mul_f32_e32 v81, v187, v81
	ds_write2st64_b32 v140, v80, v81 offset0:22 offset1:23
	v_mul_f32_e32 v80, v72, v134
	v_mul_f32_e32 v81, v73, v136
	v_mul_f32_e32 v80, v187, v80
	v_mul_f32_e32 v81, v187, v81
	ds_write2st64_b32 v140, v80, v81 offset0:24 offset1:25
	v_mul_f32_e32 v80, v74, v137
	v_mul_f32_e32 v81, v75, v138
	v_mul_f32_e32 v80, v187, v80
	v_mul_f32_e32 v81, v187, v81
	ds_write2st64_b32 v140, v80, v81 offset0:26 offset1:27
	v_mul_f32_e32 v80, v76, v139
	v_mul_f32_e32 v81, v77, v141
	v_mul_f32_e32 v80, v187, v80
	v_mul_f32_e32 v81, v187, v81
	ds_write2st64_b32 v140, v80, v81 offset0:28 offset1:29
	v_mul_f32_e32 v80, v78, v143
	v_mul_f32_e32 v81, v79, v147
	v_mul_f32_e32 v80, v187, v80
	v_mul_f32_e32 v81, v187, v81
	ds_write2st64_b32 v140, v80, v81 offset0:30 offset1:31
	v_mul_f32_e32 v80, v32, v110
	v_mul_f32_e32 v81, v33, v111
	v_mul_f32_e32 v80, v187, v80
	v_mul_f32_e32 v81, v187, v81
	ds_write2st64_b32 v140, v80, v81 offset0:32 offset1:33
	v_mul_f32_e32 v80, v34, v112
	v_mul_f32_e32 v81, v35, v113
	v_mul_f32_e32 v80, v187, v80
	v_mul_f32_e32 v81, v187, v81
	ds_write2st64_b32 v140, v80, v81 offset0:34 offset1:35
	v_mul_f32_e32 v80, v36, v114
	v_mul_f32_e32 v81, v37, v115
	v_mul_f32_e32 v80, v187, v80
	v_mul_f32_e32 v81, v187, v81
	ds_write2st64_b32 v140, v80, v81 offset0:36 offset1:37
	v_mul_f32_e32 v80, v38, v116
	v_mul_f32_e32 v81, v39, v120
	v_mul_f32_e32 v80, v187, v80
	v_mul_f32_e32 v81, v187, v81
	ds_write2st64_b32 v140, v80, v81 offset0:38 offset1:39
	v_mul_f32_e32 v80, v40, v134
	v_mul_f32_e32 v81, v41, v136
	v_mul_f32_e32 v80, v187, v80
	v_mul_f32_e32 v81, v187, v81
	ds_write2st64_b32 v140, v80, v81 offset0:40 offset1:41
	v_mul_f32_e32 v80, v42, v137
	v_mul_f32_e32 v81, v43, v138
	v_mul_f32_e32 v80, v187, v80
	v_mul_f32_e32 v81, v187, v81
	ds_write2st64_b32 v140, v80, v81 offset0:42 offset1:43
	v_mul_f32_e32 v80, v44, v139
	v_mul_f32_e32 v81, v45, v141
	v_mul_f32_e32 v80, v187, v80
	v_mul_f32_e32 v81, v187, v81
	ds_write2st64_b32 v140, v80, v81 offset0:44 offset1:45
	v_mul_f32_e32 v80, v46, v143
	v_mul_f32_e32 v81, v47, v147
	v_mul_f32_e32 v80, v187, v80
	v_mul_f32_e32 v81, v187, v81
	ds_write2st64_b32 v140, v80, v81 offset0:46 offset1:47
	v_mul_f32_e32 v80, v16, v110
	v_mul_f32_e32 v81, v17, v111
	v_mul_f32_e32 v80, v187, v80
	v_mul_f32_e32 v81, v187, v81
	ds_write2st64_b32 v140, v80, v81 offset0:48 offset1:49
	v_mul_f32_e32 v80, v18, v112
	v_mul_f32_e32 v81, v19, v113
	v_mul_f32_e32 v80, v187, v80
	v_mul_f32_e32 v81, v187, v81
	ds_write2st64_b32 v140, v80, v81 offset0:50 offset1:51
	v_mul_f32_e32 v80, v20, v114
	v_mul_f32_e32 v81, v21, v115
	v_mul_f32_e32 v80, v187, v80
	v_mul_f32_e32 v81, v187, v81
	ds_write2st64_b32 v140, v80, v81 offset0:52 offset1:53
	v_mul_f32_e32 v80, v22, v116
	v_mul_f32_e32 v81, v23, v120
	v_mul_f32_e32 v80, v187, v80
	v_mul_f32_e32 v81, v187, v81
	ds_write2st64_b32 v140, v80, v81 offset0:54 offset1:55
	v_mul_f32_e32 v80, v24, v134
	v_mul_f32_e32 v81, v25, v136
	v_mul_f32_e32 v80, v187, v80
	v_mul_f32_e32 v81, v187, v81
	ds_write2st64_b32 v140, v80, v81 offset0:56 offset1:57
	v_mul_f32_e32 v80, v26, v137
	v_mul_f32_e32 v81, v27, v138
	v_mul_f32_e32 v80, v187, v80
	v_mul_f32_e32 v81, v187, v81
	ds_write2st64_b32 v140, v80, v81 offset0:58 offset1:59
	v_mul_f32_e32 v80, v28, v139
	v_mul_f32_e32 v81, v29, v141
	v_mul_f32_e32 v80, v187, v80
	v_mul_f32_e32 v81, v187, v81
	ds_write2st64_b32 v140, v80, v81 offset0:60 offset1:61
	v_mul_f32_e32 v80, v30, v143
	v_mul_f32_e32 v81, v31, v147
	v_mul_f32_e32 v80, v187, v80
	v_mul_f32_e32 v81, v187, v81
	ds_write2st64_b32 v140, v80, v81 offset0:62 offset1:63
; template <int MODE>
; __device__ __forceinline__ void attn_unit(const Tensors& T0, int ureq, int b, int hh, int qblk, LAS3 char* shm, const bool dummy = false) {
;     ...
;     if (sub == 0 && !dummy) {
;       float ss[16];
; #pragma unroll
;       for (int r = 0; r < 16; ++r) { float s = 0.f;
; #pragma unroll
;         for (int d = 0; d < ND; ++d) { const float v = o[d][r] * rli[r] - X[(d * 16 + r) * 64 + lane]; o[d][r] = v; s += v * v; }
;         s += __shfl_xor(s, 1); s += __shfl_xor(s, 2); s += __shfl_xor(s, 4); s += __shfl_xor(s, 8); s += __shfl_xor(s, 16);
;         ss[r] = 0.8f / sqrtf(s * (1.0f / 128.0f) + 1e-6f); }
.LBB0_142:
	s_waitcnt lgkmcnt(0)
	s_barrier
	s_andn2_b64 vcc, exec, s[4:5]
	s_cbranch_vccnz .LBB0_82
	v_and_b32_e32 v81, 64, v185
	v_xor_b32_e32 v80, 1, v185
	v_add_u32_e32 v117, 64, v81
	v_cmp_lt_i32_e32 vcc, v80, v117
	s_nop 1
	v_cndmask_b32_e32 v80, v185, v80, vcc
	v_lshlrev_b32_e32 v153, 2, v80
	ds_read2st64_b32 v[80:81], v140 offset1:1
	ds_read2st64_b32 v[82:83], v140 offset0:16 offset1:17
	ds_read2st64_b32 v[84:85], v140 offset0:2 offset1:3
	ds_read2st64_b32 v[92:93], v140 offset0:4 offset1:5
	ds_read2st64_b32 v[86:87], v140 offset0:6 offset1:7
	ds_read2st64_b32 v[118:119], v140 offset0:18 offset1:19
	ds_read2st64_b32 v[132:133], v140 offset0:20 offset1:21
	ds_read2st64_b32 v[88:89], v140 offset0:22 offset1:23
	ds_read2st64_b32 v[128:129], v140 offset0:32 offset1:33
	ds_read2st64_b32 v[130:131], v140 offset0:34 offset1:35
	ds_read2st64_b32 v[144:145], v140 offset0:36 offset1:37
	ds_read2st64_b32 v[90:91], v140 offset0:38 offset1:39
	ds_read2st64_b32 v[156:157], v140 offset0:48 offset1:49
	s_waitcnt lgkmcnt(0)
	v_fma_f32 v149, v64, v110, -v82
	v_fma_f32 v189, v48, v110, -v80
	v_mul_f32_e32 v48, v149, v149
	v_fmac_f32_e32 v48, v189, v189
	s_waitcnt lgkmcnt(0)
	v_fma_f32 v127, v32, v110, -v128
	v_fmac_f32_e32 v48, v127, v127
	s_waitcnt lgkmcnt(0)
	v_fma_f32 v110, v16, v110, -v156
	v_fmac_f32_e32 v48, v110, v110
	s_nop 1
	v_mov_b32_dpp v16, v48 quad_perm:[1,0,3,2] row_mask:0xf bank_mask:0xf
	v_xor_b32_e32 v32, 2, v185
	v_cmp_lt_i32_e32 vcc, v32, v117
	v_fma_f32 v151, v65, v111, -v83
	v_fma_f32 v80, v49, v111, -v81
	v_cndmask_b32_e32 v32, v185, v32, vcc
	v_lshlrev_b32_e32 v155, 2, v32
	s_waitcnt lgkmcnt(0)
	v_add_f32_e32 v16, v48, v16
	s_nop 1
	v_mov_b32_dpp v32, v16 quad_perm:[2,3,0,1] row_mask:0xf bank_mask:0xf
	v_xor_b32_e32 v48, 4, v185
	v_cmp_lt_i32_e32 vcc, v48, v117
	v_mul_f32_e32 v49, v151, v151
	v_fmac_f32_e32 v49, v80, v80
	v_cndmask_b32_e32 v48, v185, v48, vcc
	v_lshlrev_b32_e32 v156, 2, v48
	s_waitcnt lgkmcnt(0)
	v_add_f32_e32 v16, v16, v32
	s_nop 1
	v_mov_b32_dpp v32, v16 row_half_mirror row_mask:0xf bank_mask:0xf
	v_xor_b32_e32 v48, 8, v185
	v_cmp_lt_i32_e32 vcc, v48, v117
	v_fma_f32 v128, v33, v111, -v129
	v_fmac_f32_e32 v49, v128, v128
	v_cndmask_b32_e32 v48, v185, v48, vcc
	v_lshlrev_b32_e32 v190, 2, v48
	s_waitcnt lgkmcnt(0)
	v_add_f32_e32 v16, v16, v32
	s_nop 1
	v_mov_b32_dpp v32, v16 row_mirror row_mask:0xf bank_mask:0xf
	v_xor_b32_e32 v48, 16, v185
	v_cmp_lt_i32_e32 vcc, v48, v117
	v_fma_f32 v111, v17, v111, -v157
	v_fmac_f32_e32 v49, v111, v111
	v_cndmask_b32_e32 v48, v185, v48, vcc
	v_lshlrev_b32_e32 v64, 2, v48
	s_waitcnt lgkmcnt(0)
	v_add_f32_e32 v16, v16, v32
	v_mov_b32_e32 v32, v16
	s_nop 1
	v_permlane16_swap_b32_e32 v32, v16
	s_nop 1
	v_mov_b32_dpp v17, v49 quad_perm:[1,0,3,2] row_mask:0xf bank_mask:0xf
	ds_read2st64_b32 v[158:159], v140 offset0:50 offset1:51
	ds_read2st64_b32 v[160:161], v140 offset0:52 offset1:53
	ds_read2st64_b32 v[94:95], v140 offset0:54 offset1:55
	v_fma_f32 v152, v66, v112, -v118
	v_fma_f32 v129, v34, v112, -v130
	s_waitcnt lgkmcnt(0)
	v_add_f32_e32 v16, v16, v32
	v_fmamk_f32 v16, v16, 0x3c000000, v182
	v_mul_f32_e32 v32, 0x4f800000, v16
	v_cmp_gt_f32_e32 vcc, s87, v16
	s_waitcnt lgkmcnt(0)
	v_add_f32_e32 v17, v49, v17
	s_nop 1
	v_mov_b32_dpp v49, v17 quad_perm:[2,3,0,1] row_mask:0xf bank_mask:0xf
	v_cndmask_b32_e32 v16, v16, v32, vcc
	v_sqrt_f32_e32 v32, v16
	v_fma_f32 v154, v67, v113, -v119
	v_fma_f32 v130, v35, v113, -v131
	s_waitcnt lgkmcnt(0)
	v_add_f32_e32 v17, v17, v49
	v_add_u32_e32 v48, -1, v32
	v_fma_f32 v82, -v48, v32, v16
	v_cmp_ge_f32_e64 s[4:5], 0, v82
	v_fma_f32 v157, v68, v114, -v132
	v_fma_f32 v131, v36, v114, -v144
	v_cndmask_b32_e64 v33, v32, v48, s[4:5]
	v_add_u32_e32 v48, 1, v32
	v_fma_f32 v32, -v48, v32, v16
	v_cmp_lt_f32_e64 s[4:5], 0, v32
	v_fma_f32 v132, v37, v115, -v145
	v_fma_f32 v135, v39, v120, -v91
	v_cndmask_b32_e64 v32, v33, v48, s[4:5]
	v_mul_f32_e32 v33, 0x37800000, v32
	v_cndmask_b32_e32 v32, v32, v33, vcc
	v_cmp_class_f32_e32 vcc, v16, v183
	s_nop 1
	v_mov_b32_dpp v33, v17 row_half_mirror row_mask:0xf bank_mask:0xf
	s_waitcnt lgkmcnt(0)
	v_add_f32_e32 v33, v17, v33
	v_cndmask_b32_e32 v32, v32, v16, vcc
	s_nop 1
	v_mov_b32_dpp v65, v33 row_mirror row_mask:0xf bank_mask:0xf
	v_lshl_add_u64 v[16:17], v[96:97], 0, s[54:55]
	v_fma_f32 v81, v50, v112, -v84
	v_mul_f32_e32 v50, v152, v152
	v_fmac_f32_e32 v50, v81, v81
	v_fmac_f32_e32 v50, v129, v129
	v_fma_f32 v112, v18, v112, -v158
	v_fmac_f32_e32 v50, v112, v112
	s_nop 1
	v_mov_b32_dpp v18, v50 quad_perm:[1,0,3,2] row_mask:0xf bank_mask:0xf
	s_waitcnt lgkmcnt(0)
	v_add_f32_e32 v33, v33, v65
	v_mov_b32_e32 v65, v33
	s_nop 1
	v_permlane16_swap_b32_e32 v65, v33
	v_fma_f32 v82, v51, v113, -v85
	s_waitcnt lgkmcnt(0)
	v_add_f32_e32 v18, v50, v18
	s_nop 1
	v_mov_b32_dpp v50, v18 quad_perm:[2,3,0,1] row_mask:0xf bank_mask:0xf
	s_waitcnt lgkmcnt(0)
	v_add_f32_e32 v33, v33, v65
	v_fmamk_f32 v33, v33, 0x3c000000, v182
	v_mul_f32_e32 v65, 0x4f800000, v33
	v_cmp_gt_f32_e64 s[4:5], s87, v33
	s_waitcnt lgkmcnt(0)
	v_add_f32_e32 v18, v18, v50
	s_nop 1
	v_mov_b32_dpp v50, v18 row_half_mirror row_mask:0xf bank_mask:0xf
	v_cndmask_b32_e64 v33, v33, v65, s[4:5]
	v_sqrt_f32_e32 v65, v33
	v_mul_f32_e32 v51, v154, v154
	v_fmac_f32_e32 v51, v82, v82
	s_waitcnt lgkmcnt(0)
	v_add_f32_e32 v18, v18, v50
	v_add_u32_e32 v83, -1, v65
	s_nop 1
	v_mov_b32_dpp v50, v18 row_mirror row_mask:0xf bank_mask:0xf
	v_fma_f32 v117, -v83, v65, v33
	v_cmp_ge_f32_e64 s[6:7], 0, v117
	v_add_u32_e32 v66, 1, v65
	v_rcp_f32_e32 v117, v32
	s_nop 0
	v_mul_f32_e32 v117, s88, v117
	v_cndmask_b32_e64 v34, v65, v83, s[6:7]
	v_fma_f32 v65, -v66, v65, v33
	v_cmp_lt_f32_e64 s[6:7], 0, v65
	s_waitcnt lgkmcnt(0)
; template <int MODE>
; __device__ __forceinline__ void attn_unit(const Tensors& T0, int ureq, int b, int hh, int qblk, LAS3 char* shm, const bool dummy = false) {
;     ...
;       for (int r = 0; r < 16; ++r) { float s = 0.f;
; #pragma unroll
;         for (int d = 0; d < ND; ++d) { const float v = o[d][r] * rli[r] - X[(d * 16 + r) * 64 + lane]; o[d][r] = v; s += v * v; }
;         s += __shfl_xor(s, 1); s += __shfl_xor(s, 2); s += __shfl_xor(s, 4); s += __shfl_xor(s, 8); s += __shfl_xor(s, 16);
;         ss[r] = 0.8f / sqrtf(s * (1.0f / 128.0f) + 1e-6f); }
	v_add_f32_e32 v18, v18, v50
	v_mov_b32_e32 v48, v18
	s_nop 1
	v_permlane16_swap_b32_e32 v48, v18
	v_cndmask_b32_e64 v34, v34, v66, s[6:7]
	v_mul_f32_e32 v65, 0x37800000, v34
	v_cndmask_b32_e64 v34, v34, v65, s[4:5]
	v_cmp_class_f32_e64 s[4:5], v33, v183
	s_waitcnt lgkmcnt(0)
	v_add_f32_e32 v18, v18, v48
	v_fmamk_f32 v18, v18, 0x3c000000, v182
	v_cndmask_b32_e64 v33, v34, v33, s[4:5]
	v_mul_f32_e32 v48, 0x4f800000, v18
	v_cmp_gt_f32_e64 s[4:5], s87, v18
	v_fmac_f32_e32 v51, v130, v130
	v_fma_f32 v113, v19, v113, -v159
	v_cndmask_b32_e64 v18, v18, v48, s[4:5]
	v_fmac_f32_e32 v51, v113, v113
	v_sqrt_f32_e32 v48, v18
	s_nop 1
	v_mov_b32_dpp v19, v51 quad_perm:[1,0,3,2] row_mask:0xf bank_mask:0xf
	v_add_u32_e32 v34, -1, v48
	v_fma_f32 v50, -v34, v48, v18
	s_waitcnt lgkmcnt(0)
	v_add_f32_e32 v19, v51, v19
	v_cmp_ge_f32_e64 s[6:7], 0, v50
	s_nop 1
	v_mov_b32_dpp v50, v19 quad_perm:[2,3,0,1] row_mask:0xf bank_mask:0xf
	v_add_u32_e32 v35, 1, v48
	v_cndmask_b32_e64 v34, v48, v34, s[6:7]
	v_fma_f32 v48, -v35, v48, v18
	v_cmp_lt_f32_e64 s[6:7], 0, v48
	s_waitcnt lgkmcnt(0)
	v_add_f32_e32 v19, v19, v50
	v_cndmask_b32_e64 v34, v34, v35, s[6:7]
	v_mul_f32_e32 v35, 0x37800000, v34
	v_cndmask_b32_e64 v34, v34, v35, s[4:5]
	s_nop 1
	v_mov_b32_dpp v35, v19 row_half_mirror row_mask:0xf bank_mask:0xf
	v_rcp_f32_e32 v118, v33
	s_nop 0
	v_mul_f32_e32 v118, s88, v118
	v_cmp_class_f32_e64 s[4:5], v18, v183
	v_fma_f32 v83, v52, v114, -v92
	v_mul_f32_e32 v50, v157, v157
	s_waitcnt lgkmcnt(0)
	v_add_f32_e32 v19, v19, v35
	s_nop 1
	v_mov_b32_dpp v35, v19 row_mirror row_mask:0xf bank_mask:0xf
	v_cndmask_b32_e64 v18, v34, v18, s[4:5]
	s_waitcnt lgkmcnt(0)
	v_add_f32_e32 v19, v19, v35
	v_mov_b32_e32 v33, v19
	s_nop 1
	v_permlane16_swap_b32_e32 v33, v19
	v_fmac_f32_e32 v50, v83, v83
	v_fmac_f32_e32 v50, v131, v131
	v_fma_f32 v114, v20, v114, -v160
	s_waitcnt lgkmcnt(0)
	v_add_f32_e32 v19, v19, v33
	v_fmamk_f32 v19, v19, 0x3c000000, v182
	v_mul_f32_e32 v33, 0x4f800000, v19
	v_cmp_gt_f32_e64 s[4:5], s87, v19
	v_fmac_f32_e32 v50, v114, v114
	s_nop 0
	v_cndmask_b32_e64 v19, v19, v33, s[4:5]
	v_sqrt_f32_e32 v33, v19
	s_nop 1
	v_mov_b32_dpp v20, v50 quad_perm:[1,0,3,2] row_mask:0xf bank_mask:0xf
	v_add_u32_e32 v34, -1, v33
	v_fma_f32 v49, -v34, v33, v19
	s_waitcnt lgkmcnt(0)
	v_add_f32_e32 v20, v50, v20
	v_cmp_ge_f32_e64 s[6:7], 0, v49
	s_nop 1
	v_mov_b32_dpp v49, v20 quad_perm:[2,3,0,1] row_mask:0xf bank_mask:0xf
	v_add_u32_e32 v36, 1, v33
	v_cndmask_b32_e64 v34, v33, v34, s[6:7]
	v_fma_f32 v33, -v36, v33, v19
	v_cmp_lt_f32_e64 s[6:7], 0, v33
	s_waitcnt lgkmcnt(0)
	v_add_f32_e32 v20, v20, v49
	v_cndmask_b32_e64 v33, v34, v36, s[6:7]
	v_mul_f32_e32 v34, 0x37800000, v33
	v_cndmask_b32_e64 v33, v33, v34, s[4:5]
	s_nop 1
	v_mov_b32_dpp v34, v20 row_half_mirror row_mask:0xf bank_mask:0xf
	v_rcp_f32_e32 v119, v18
	s_nop 0
	v_mul_f32_e32 v119, s88, v119
	v_cmp_class_f32_e64 s[4:5], v19, v183
	v_fma_f32 v158, v69, v115, -v133
	v_fma_f32 v84, v53, v115, -v93
	s_waitcnt lgkmcnt(0)
	v_add_f32_e32 v20, v20, v34
	s_nop 1
	v_mov_b32_dpp v34, v20 row_mirror row_mask:0xf bank_mask:0xf
	v_cndmask_b32_e64 v19, v33, v19, s[4:5]
	s_waitcnt lgkmcnt(0)
	v_add_f32_e32 v20, v20, v34
	v_mov_b32_e32 v32, v20
	s_nop 1
	v_permlane16_swap_b32_e32 v32, v20
	v_mul_f32_e32 v48, v158, v158
	v_fmac_f32_e32 v48, v84, v84
	v_fmac_f32_e32 v48, v132, v132
	v_fma_f32 v115, v21, v115, -v161
	s_waitcnt lgkmcnt(0)
	v_add_f32_e32 v20, v20, v32
	v_fmamk_f32 v20, v20, 0x3c000000, v182
	v_mul_f32_e32 v32, 0x4f800000, v20
	v_cmp_gt_f32_e64 s[4:5], s87, v20
	v_fmac_f32_e32 v48, v115, v115
	s_nop 0
	v_cndmask_b32_e64 v20, v20, v32, s[4:5]
	s_nop 1
	v_mov_b32_dpp v21, v48 quad_perm:[1,0,3,2] row_mask:0xf bank_mask:0xf
	v_sqrt_f32_e32 v32, v20
	s_nop 0
	v_add_u32_e32 v33, -1, v32
	s_waitcnt lgkmcnt(0)
	v_add_f32_e32 v21, v48, v21
	v_fma_f32 v35, -v33, v32, v20
	s_nop 1
	v_mov_b32_dpp v37, v21 quad_perm:[2,3,0,1] row_mask:0xf bank_mask:0xf
	v_cmp_ge_f32_e64 s[6:7], 0, v35
	v_add_u32_e32 v35, 1, v32
	s_nop 0
	v_cndmask_b32_e64 v33, v32, v33, s[6:7]
	v_fma_f32 v32, -v35, v32, v20
	v_cmp_lt_f32_e64 s[6:7], 0, v32
	s_waitcnt lgkmcnt(0)
	v_add_f32_e32 v21, v21, v37
	v_rcp_f32_e32 v122, v19
	s_nop 0
	v_mul_f32_e32 v122, s88, v122
	v_cndmask_b32_e64 v32, v33, v35, s[6:7]
	v_mul_f32_e32 v33, 0x37800000, v32
	v_cndmask_b32_e64 v32, v32, v33, s[4:5]
	s_nop 1
	v_mov_b32_dpp v33, v21 row_half_mirror row_mask:0xf bank_mask:0xf
	v_cmp_class_f32_e64 s[4:5], v20, v183
	v_fma_f32 v159, v70, v116, -v88
	v_fma_f32 v85, v54, v116, -v86
	v_cndmask_b32_e64 v20, v32, v20, s[4:5]
	s_waitcnt lgkmcnt(0)
	v_add_f32_e32 v21, v21, v33
	s_nop 1
	v_mov_b32_dpp v33, v21 row_mirror row_mask:0xf bank_mask:0xf
	v_mul_f32_e32 v36, v159, v159
	s_waitcnt lgkmcnt(0)
	v_add_f32_e32 v19, v21, v33
	v_mov_b32_e32 v21, v19
	s_nop 1
	v_permlane16_swap_b32_e32 v21, v19
	v_fmac_f32_e32 v36, v85, v85
	v_fma_f32 v133, v38, v116, -v90
	v_fmac_f32_e32 v36, v133, v133
	v_fma_f32 v116, v22, v116, -v94
	s_waitcnt lgkmcnt(0)
	v_add_f32_e32 v19, v19, v21
	v_fmamk_f32 v19, v19, 0x3c000000, v182
	v_mul_f32_e32 v21, 0x4f800000, v19
	v_cmp_gt_f32_e64 s[4:5], s87, v19
	v_fmac_f32_e32 v36, v116, v116
	s_nop 0
	v_cndmask_b32_e64 v19, v19, v21, s[4:5]
	s_nop 1
	v_mov_b32_dpp v22, v36 quad_perm:[1,0,3,2] row_mask:0xf bank_mask:0xf
	v_sqrt_f32_e32 v21, v19
	s_nop 0
	v_add_u32_e32 v32, -1, v21
	s_waitcnt lgkmcnt(0)
	v_add_f32_e32 v22, v36, v22
	v_fma_f32 v34, -v32, v21, v19
	s_nop 1
	v_mov_b32_dpp v36, v22 quad_perm:[2,3,0,1] row_mask:0xf bank_mask:0xf
	v_cmp_ge_f32_e64 s[6:7], 0, v34
	v_add_u32_e32 v34, 1, v21
	s_nop 0
	v_cndmask_b32_e64 v32, v21, v32, s[6:7]
	v_fma_f32 v21, -v34, v21, v19
	v_cmp_lt_f32_e64 s[6:7], 0, v21
	s_waitcnt lgkmcnt(0)
; template <int MODE>
; __device__ __forceinline__ void attn_unit(const Tensors& T0, int ureq, int b, int hh, int qblk, LAS3 char* shm, const bool dummy = false) {
;     ...
;       for (int r = 0; r < 16; ++r) { float s = 0.f;
; #pragma unroll
;         for (int d = 0; d < ND; ++d) { const float v = o[d][r] * rli[r] - X[(d * 16 + r) * 64 + lane]; o[d][r] = v; s += v * v; }
;         s += __shfl_xor(s, 1); s += __shfl_xor(s, 2); s += __shfl_xor(s, 4); s += __shfl_xor(s, 8); s += __shfl_xor(s, 16);
;         ss[r] = 0.8f / sqrtf(s * (1.0f / 128.0f) + 1e-6f); }
	v_add_f32_e32 v22, v22, v36
	v_rcp_f32_e32 v124, v20
	s_nop 0
	v_mul_f32_e32 v124, s88, v124
	v_cndmask_b32_e64 v21, v32, v34, s[6:7]
	v_mul_f32_e32 v32, 0x37800000, v21
	v_cndmask_b32_e64 v21, v21, v32, s[4:5]
	s_nop 1
	v_mov_b32_dpp v32, v22 row_half_mirror row_mask:0xf bank_mask:0xf
	v_cmp_class_f32_e64 s[4:5], v19, v183
	v_fma_f32 v160, v71, v120, -v89
	v_fma_f32 v86, v55, v120, -v87
	v_cndmask_b32_e64 v19, v21, v19, s[4:5]
	s_waitcnt lgkmcnt(0)
	v_add_f32_e32 v22, v22, v32
	s_nop 1
	v_mov_b32_dpp v32, v22 row_mirror row_mask:0xf bank_mask:0xf
	v_mul_f32_e32 v35, v160, v160
	s_waitcnt lgkmcnt(0)
	v_add_f32_e32 v20, v22, v32
	v_mov_b32_e32 v22, v20
	s_nop 1
	v_permlane16_swap_b32_e32 v22, v20
	v_fmac_f32_e32 v35, v86, v86
	v_fmac_f32_e32 v35, v135, v135
	v_fma_f32 v120, v23, v120, -v95
	s_waitcnt lgkmcnt(0)
	v_add_f32_e32 v20, v20, v22
	v_fmamk_f32 v20, v20, 0x3c000000, v182
	v_mul_f32_e32 v22, 0x4f800000, v20
	v_cmp_gt_f32_e64 s[4:5], s87, v20
	v_fmac_f32_e32 v35, v120, v120
	s_nop 0
	v_cndmask_b32_e64 v20, v20, v22, s[4:5]
	v_sqrt_f32_e32 v22, v20
	s_nop 1
	v_mov_b32_dpp v23, v35 quad_perm:[1,0,3,2] row_mask:0xf bank_mask:0xf
	v_add_u32_e32 v21, -1, v22
	v_fma_f32 v33, -v21, v22, v20
	s_waitcnt lgkmcnt(0)
	v_add_f32_e32 v23, v35, v23
	v_cmp_ge_f32_e64 s[6:7], 0, v33
	v_add_u32_e32 v33, 1, v22
	s_nop 1
	v_mov_b32_dpp v35, v23 quad_perm:[2,3,0,1] row_mask:0xf bank_mask:0xf
	v_cndmask_b32_e64 v21, v22, v21, s[6:7]
	v_fma_f32 v22, -v33, v22, v20
	v_cmp_lt_f32_e64 s[6:7], 0, v22
	v_rcp_f32_e32 v126, v19
	s_nop 0
	v_mul_f32_e32 v126, s88, v126
	v_cndmask_b32_e64 v21, v21, v33, s[6:7]
	v_mul_f32_e32 v22, 0x37800000, v21
	v_cndmask_b32_e64 v21, v21, v22, s[4:5]
	s_waitcnt lgkmcnt(0)
	v_add_f32_e32 v22, v23, v35
	s_nop 1
	v_mov_b32_dpp v23, v22 row_half_mirror row_mask:0xf bank_mask:0xf
	v_cmp_class_f32_e64 s[4:5], v20, v183
	v_mul_f32_e32 v80, v80, v118
	s_nop 0
	v_cndmask_b32_e64 v65, v21, v20, s[4:5]
	s_waitcnt lgkmcnt(0)
	v_add_f32_e32 v21, v22, v23
	s_nop 1
	v_mov_b32_dpp v22, v21 row_mirror row_mask:0xf bank_mask:0xf
	s_waitcnt lgkmcnt(0)
	v_add_f32_e32 v19, v21, v22
	v_mov_b32_e32 v21, v19
	s_nop 1
	v_permlane16_swap_b32_e32 v21, v19
	s_waitcnt lgkmcnt(0)
	v_add_f32_e32 v19, v19, v21
	v_fmamk_f32 v19, v19, 0x3c000000, v182
	v_mul_f32_e32 v21, 0x4f800000, v19
	v_cmp_gt_f32_e64 s[4:5], s87, v19
	s_nop 1
	v_cndmask_b32_e64 v94, v19, v21, s[4:5]
	ds_read2st64_b32 v[18:19], v140 offset0:8 offset1:9
	ds_read2st64_b32 v[20:21], v140 offset0:24 offset1:25
	ds_read2st64_b32 v[22:23], v140 offset0:10 offset1:11
	ds_read2st64_b32 v[38:39], v140 offset0:12 offset1:13
	ds_read2st64_b32 v[32:33], v140 offset0:14 offset1:15
	ds_read2st64_b32 v[50:51], v140 offset0:26 offset1:27
	ds_read2st64_b32 v[52:53], v140 offset0:28 offset1:29
	ds_read2st64_b32 v[34:35], v140 offset0:30 offset1:31
	ds_read2st64_b32 v[54:55], v140 offset0:40 offset1:41
	ds_read2st64_b32 v[66:67], v140 offset0:42 offset1:43
	ds_read2st64_b32 v[68:69], v140 offset0:44 offset1:45
	ds_read2st64_b32 v[36:37], v140 offset0:46 offset1:47
	ds_read2st64_b32 v[70:71], v140 offset0:56 offset1:57
	s_waitcnt lgkmcnt(0)
	v_fma_f32 v169, v72, v134, -v20
	v_fma_f32 v87, v56, v134, -v18
	v_mul_f32_e32 v18, v169, v169
	v_fmac_f32_e32 v18, v87, v87
	s_waitcnt lgkmcnt(0)
	v_fma_f32 v161, v40, v134, -v54
	v_fmac_f32_e32 v18, v161, v161
	s_waitcnt lgkmcnt(0)
	v_fma_f32 v134, v24, v134, -v70
	v_fmac_f32_e32 v18, v134, v134
	s_nop 1
	v_mov_b32_dpp v20, v18 quad_perm:[1,0,3,2] row_mask:0xf bank_mask:0xf
	v_fma_f32 v170, v73, v136, -v21
	v_sqrt_f32_e32 v95, v94
	v_fma_f32 v88, v57, v136, -v19
	s_waitcnt lgkmcnt(0)
	v_add_f32_e32 v18, v18, v20
	s_nop 1
	v_mov_b32_dpp v20, v18 quad_perm:[2,3,0,1] row_mask:0xf bank_mask:0xf
	v_mul_f32_e32 v19, v170, v170
	v_fmac_f32_e32 v19, v88, v88
	v_fma_f32 v162, v41, v136, -v55
	v_fmac_f32_e32 v19, v162, v162
	s_waitcnt lgkmcnt(0)
	v_add_f32_e32 v18, v18, v20
	s_nop 1
	v_mov_b32_dpp v20, v18 row_half_mirror row_mask:0xf bank_mask:0xf
	v_fma_f32 v136, v25, v136, -v71
	v_fmac_f32_e32 v19, v136, v136
	v_add_u32_e32 v144, -1, v95
	s_nop 1
	v_mov_b32_dpp v21, v19 quad_perm:[1,0,3,2] row_mask:0xf bank_mask:0xf
	s_waitcnt lgkmcnt(0)
	v_add_f32_e32 v18, v18, v20
	s_nop 1
	v_mov_b32_dpp v20, v18 row_mirror row_mask:0xf bank_mask:0xf
	v_fma_f32 v145, -v144, v95, v94
	v_add_u32_e32 v40, 1, v95
	v_cmp_ge_f32_e64 s[6:7], 0, v145
	v_fma_f32 v54, -v40, v95, v94
	s_waitcnt lgkmcnt(0)
	v_add_f32_e32 v18, v18, v20
	v_cndmask_b32_e64 v24, v95, v144, s[6:7]
	v_cmp_lt_f32_e64 s[6:7], 0, v54
	v_mov_b32_e32 v20, v18
	s_nop 1
	v_permlane16_swap_b32_e32 v20, v18
	v_add_f32_e32 v19, v19, v21
	v_cndmask_b32_e64 v24, v24, v40, s[6:7]
	v_mul_f32_e32 v40, 0x37800000, v24
	v_cndmask_b32_e64 v24, v24, v40, s[4:5]
	v_cmp_class_f32_e64 s[4:5], v94, v183
	s_nop 1
	v_mov_b32_dpp v21, v19 quad_perm:[2,3,0,1] row_mask:0xf bank_mask:0xf
	s_waitcnt lgkmcnt(0)
	v_add_f32_e32 v18, v18, v20
	v_cndmask_b32_e64 v24, v24, v94, s[4:5]
	v_fmamk_f32 v18, v18, 0x3c000000, v182
	s_waitcnt lgkmcnt(0)
	v_add_f32_e32 v19, v19, v21
	v_mul_f32_e32 v20, 0x4f800000, v18
	v_cmp_gt_f32_e64 s[4:5], s87, v18
	s_nop 1
	v_mov_b32_dpp v21, v19 row_half_mirror row_mask:0xf bank_mask:0xf
	ds_read2st64_b32 v[90:91], v140 offset0:58 offset1:59
	ds_read2st64_b32 v[92:93], v140 offset0:60 offset1:61
	ds_read2st64_b32 v[48:49], v140 offset0:62 offset1:63
	v_rcp_f32_e32 v140, v65
	s_nop 0
	v_mul_f32_e32 v140, s88, v140
	v_cndmask_b32_e64 v18, v18, v20, s[4:5]
	v_sqrt_f32_e32 v20, v18
	s_waitcnt lgkmcnt(0)
; template <int MODE>
; __device__ __forceinline__ void attn_unit(const Tensors& T0, int ureq, int b, int hh, int qblk, LAS3 char* shm, const bool dummy = false) {
;     ...
;       for (int r = 0; r < 16; ++r) { float s = 0.f;
; #pragma unroll
;         for (int d = 0; d < ND; ++d) { const float v = o[d][r] * rli[r] - X[(d * 16 + r) * 64 + lane]; o[d][r] = v; s += v * v; }
;         s += __shfl_xor(s, 1); s += __shfl_xor(s, 2); s += __shfl_xor(s, 4); s += __shfl_xor(s, 8); s += __shfl_xor(s, 16);
;         ss[r] = 0.8f / sqrtf(s * (1.0f / 128.0f) + 1e-6f); }
	v_add_f32_e32 v19, v19, v21
	v_add_u32_e32 v56, -1, v20
	s_nop 1
	v_mov_b32_dpp v21, v19 row_mirror row_mask:0xf bank_mask:0xf
	v_fma_f32 v70, -v56, v20, v18
	v_cmp_ge_f32_e64 s[6:7], 0, v70
	v_add_u32_e32 v41, 1, v20
	v_fma_f32 v171, v74, v137, -v50
	v_cndmask_b32_e64 v25, v20, v56, s[6:7]
	v_fma_f32 v20, -v41, v20, v18
	v_cmp_lt_f32_e64 s[6:7], 0, v20
	s_waitcnt lgkmcnt(0)
	v_add_f32_e32 v19, v19, v21
	v_mov_b32_e32 v21, v19
	s_nop 1
	v_permlane16_swap_b32_e32 v21, v19
	v_cndmask_b32_e64 v20, v25, v41, s[6:7]
	v_mul_f32_e32 v25, 0x37800000, v20
	v_cndmask_b32_e64 v20, v20, v25, s[4:5]
	v_cmp_class_f32_e64 s[4:5], v18, v183
	v_fma_f32 v89, v58, v137, -v22
	v_mul_f32_e32 v22, v171, v171
	v_cndmask_b32_e64 v18, v20, v18, s[4:5]
	s_waitcnt lgkmcnt(0)
	v_add_f32_e32 v19, v19, v21
	v_fmac_f32_e32 v22, v89, v89
	v_fma_f32 v163, v42, v137, -v66
	v_fmamk_f32 v19, v19, 0x3c000000, v182
	v_fmac_f32_e32 v22, v163, v163
	v_fma_f32 v137, v26, v137, -v90
	v_mul_f32_e32 v21, 0x4f800000, v19
	v_cmp_gt_f32_e64 s[4:5], s87, v19
	v_fmac_f32_e32 v22, v137, v137
	v_rcp_f32_e32 v142, v24
	s_nop 0
	v_mul_f32_e32 v142, s88, v142
	v_cndmask_b32_e64 v19, v19, v21, s[4:5]
	s_nop 1
	v_mov_b32_dpp v26, v22 quad_perm:[1,0,3,2] row_mask:0xf bank_mask:0xf
	v_sqrt_f32_e32 v21, v19
	s_nop 0
	v_add_u32_e32 v24, -1, v21
	s_waitcnt lgkmcnt(0)
	v_add_f32_e32 v22, v22, v26
	v_fma_f32 v41, -v24, v21, v19
	s_nop 1
	v_mov_b32_dpp v26, v22 quad_perm:[2,3,0,1] row_mask:0xf bank_mask:0xf
	v_cmp_ge_f32_e64 s[6:7], 0, v41
	v_add_u32_e32 v41, 1, v21
	s_nop 0
	v_cndmask_b32_e64 v24, v21, v24, s[6:7]
	v_fma_f32 v21, -v41, v21, v19
	v_cmp_lt_f32_e64 s[6:7], 0, v21
	s_waitcnt lgkmcnt(0)
	v_add_f32_e32 v22, v22, v26
	v_rcp_f32_e32 v144, v18
	s_nop 0
	v_mul_f32_e32 v144, s88, v144
	v_cndmask_b32_e64 v21, v24, v41, s[6:7]
	v_mul_f32_e32 v24, 0x37800000, v21
	v_cndmask_b32_e64 v21, v21, v24, s[4:5]
	s_nop 1
	v_mov_b32_dpp v24, v22 row_half_mirror row_mask:0xf bank_mask:0xf
	v_cmp_class_f32_e64 s[4:5], v19, v183
	v_fma_f32 v176, v75, v138, -v51
	v_fma_f32 v90, v59, v138, -v23
	v_cndmask_b32_e64 v19, v21, v19, s[4:5]
	s_waitcnt lgkmcnt(0)
	v_add_f32_e32 v22, v22, v24
	s_nop 1
	v_mov_b32_dpp v24, v22 row_mirror row_mask:0xf bank_mask:0xf
	v_mul_f32_e32 v23, v176, v176
	s_waitcnt lgkmcnt(0)
	v_add_f32_e32 v20, v22, v24
	v_mov_b32_e32 v22, v20
	s_nop 1
	v_permlane16_swap_b32_e32 v22, v20
	v_fmac_f32_e32 v23, v90, v90
	v_fma_f32 v164, v43, v138, -v67
	v_fmac_f32_e32 v23, v164, v164
	v_fma_f32 v138, v27, v138, -v91
	s_waitcnt lgkmcnt(0)
	v_add_f32_e32 v20, v20, v22
	v_fmamk_f32 v20, v20, 0x3c000000, v182
	v_mul_f32_e32 v22, 0x4f800000, v20
	v_cmp_gt_f32_e64 s[4:5], s87, v20
	v_fmac_f32_e32 v23, v138, v138
	s_nop 0
	v_cndmask_b32_e64 v20, v20, v22, s[4:5]
	v_sqrt_f32_e32 v22, v20
	s_nop 1
	v_mov_b32_dpp v27, v23 quad_perm:[1,0,3,2] row_mask:0xf bank_mask:0xf
	v_add_u32_e32 v21, -1, v22
	v_fma_f32 v25, -v21, v22, v20
	s_waitcnt lgkmcnt(0)
	v_add_f32_e32 v23, v23, v27
	v_cmp_ge_f32_e64 s[6:7], 0, v25
	v_add_u32_e32 v25, 1, v22
	s_nop 1
	v_mov_b32_dpp v27, v23 quad_perm:[2,3,0,1] row_mask:0xf bank_mask:0xf
	v_cndmask_b32_e64 v21, v22, v21, s[6:7]
	v_fma_f32 v22, -v25, v22, v20
	v_cmp_lt_f32_e64 s[6:7], 0, v22
	v_rcp_f32_e32 v145, v19
	s_nop 0
	v_mul_f32_e32 v145, s88, v145
	v_cndmask_b32_e64 v21, v21, v25, s[6:7]
	v_mul_f32_e32 v22, 0x37800000, v21
	v_cndmask_b32_e64 v21, v21, v22, s[4:5]
	s_waitcnt lgkmcnt(0)
	v_add_f32_e32 v22, v23, v27
	s_nop 1
	v_mov_b32_dpp v23, v22 row_half_mirror row_mask:0xf bank_mask:0xf
	v_cmp_class_f32_e64 s[4:5], v20, v183
	v_fma_f32 v178, v76, v139, -v52
	v_fma_f32 v91, v60, v139, -v38
	v_cndmask_b32_e64 v20, v21, v20, s[4:5]
	s_waitcnt lgkmcnt(0)
	v_add_f32_e32 v22, v22, v23
	s_nop 1
	v_mov_b32_dpp v23, v22 row_mirror row_mask:0xf bank_mask:0xf
	v_mul_f32_e32 v26, v178, v178
	s_waitcnt lgkmcnt(0)
	v_add_f32_e32 v19, v22, v23
	v_mov_b32_e32 v22, v19
	s_nop 1
	v_permlane16_swap_b32_e32 v22, v19
	v_fmac_f32_e32 v26, v91, v91
	v_fma_f32 v165, v44, v139, -v68
	v_fmac_f32_e32 v26, v165, v165
	v_fma_f32 v139, v28, v139, -v92
	s_waitcnt lgkmcnt(0)
	v_add_f32_e32 v19, v19, v22
	v_fmamk_f32 v19, v19, 0x3c000000, v182
	v_mul_f32_e32 v22, 0x4f800000, v19
	v_cmp_gt_f32_e64 s[4:5], s87, v19
	v_fmac_f32_e32 v26, v139, v139
	s_nop 0
	v_cndmask_b32_e64 v19, v19, v22, s[4:5]
	v_sqrt_f32_e32 v22, v19
	s_nop 1
	v_mov_b32_dpp v27, v26 quad_perm:[1,0,3,2] row_mask:0xf bank_mask:0xf
	v_add_u32_e32 v21, -1, v22
	v_fma_f32 v24, -v21, v22, v19
	s_waitcnt lgkmcnt(0)
	v_add_f32_e32 v26, v26, v27
	v_cmp_ge_f32_e64 s[6:7], 0, v24
	v_add_u32_e32 v24, 1, v22
	s_nop 1
	v_mov_b32_dpp v27, v26 quad_perm:[2,3,0,1] row_mask:0xf bank_mask:0xf
	v_cndmask_b32_e64 v21, v22, v21, s[6:7]
	v_fma_f32 v22, -v24, v22, v19
	v_cmp_lt_f32_e64 s[6:7], 0, v22
	v_rcp_f32_e32 v146, v20
	s_nop 0
	v_mul_f32_e32 v146, s88, v146
	v_cndmask_b32_e64 v21, v21, v24, s[6:7]
	v_mul_f32_e32 v22, 0x37800000, v21
	v_cndmask_b32_e64 v21, v21, v22, s[4:5]
	s_waitcnt lgkmcnt(0)
	v_add_f32_e32 v22, v26, v27
	s_nop 1
	v_mov_b32_dpp v24, v22 row_half_mirror row_mask:0xf bank_mask:0xf
	v_cmp_class_f32_e64 s[4:5], v19, v183
	v_fma_f32 v179, v77, v141, -v53
	v_fma_f32 v92, v61, v141, -v39
	v_cndmask_b32_e64 v19, v21, v19, s[4:5]
	s_waitcnt lgkmcnt(0)
	v_add_f32_e32 v22, v22, v24
	s_nop 1
	v_mov_b32_dpp v24, v22 row_mirror row_mask:0xf bank_mask:0xf
	v_mul_f32_e32 v25, v179, v179
	s_waitcnt lgkmcnt(0)
	v_add_f32_e32 v20, v22, v24
	v_mov_b32_e32 v22, v20
	s_nop 1
	v_permlane16_swap_b32_e32 v22, v20
	v_fmac_f32_e32 v25, v92, v92
	v_fma_f32 v166, v45, v141, -v69
	v_fmac_f32_e32 v25, v166, v166
	v_fma_f32 v141, v29, v141, -v93
	s_waitcnt lgkmcnt(0)
; template <int MODE>
; __device__ __forceinline__ void attn_unit(const Tensors& T0, int ureq, int b, int hh, int qblk, LAS3 char* shm, const bool dummy = false) {
;     ...
;       for (int r = 0; r < 16; ++r) { float s = 0.f;
; #pragma unroll
;         for (int d = 0; d < ND; ++d) { const float v = o[d][r] * rli[r] - X[(d * 16 + r) * 64 + lane]; o[d][r] = v; s += v * v; }
;         s += __shfl_xor(s, 1); s += __shfl_xor(s, 2); s += __shfl_xor(s, 4); s += __shfl_xor(s, 8); s += __shfl_xor(s, 16);
;         ss[r] = 0.8f / sqrtf(s * (1.0f / 128.0f) + 1e-6f); }
	v_add_f32_e32 v20, v20, v22
	v_fmamk_f32 v20, v20, 0x3c000000, v182
	v_mul_f32_e32 v22, 0x4f800000, v20
	v_cmp_gt_f32_e64 s[4:5], s87, v20
	v_fmac_f32_e32 v25, v141, v141
	s_nop 0
	v_cndmask_b32_e64 v20, v20, v22, s[4:5]
	v_sqrt_f32_e32 v22, v20
	s_nop 1
	v_mov_b32_dpp v27, v25 quad_perm:[1,0,3,2] row_mask:0xf bank_mask:0xf
	v_add_u32_e32 v21, -1, v22
	v_fma_f32 v24, -v21, v22, v20
	s_waitcnt lgkmcnt(0)
	v_add_f32_e32 v25, v25, v27
	v_cmp_ge_f32_e64 s[6:7], 0, v24
	v_add_u32_e32 v24, 1, v22
	s_nop 1
	v_mov_b32_dpp v27, v25 quad_perm:[2,3,0,1] row_mask:0xf bank_mask:0xf
	v_cndmask_b32_e64 v21, v22, v21, s[6:7]
	v_fma_f32 v22, -v24, v22, v20
	v_cmp_lt_f32_e64 s[6:7], 0, v22
	v_rcp_f32_e32 v148, v19
	s_nop 0
	v_mul_f32_e32 v148, s88, v148
	v_cndmask_b32_e64 v21, v21, v24, s[6:7]
	v_mul_f32_e32 v22, 0x37800000, v21
	v_cndmask_b32_e64 v21, v21, v22, s[4:5]
	s_waitcnt lgkmcnt(0)
	v_add_f32_e32 v22, v25, v27
	s_nop 1
	v_mov_b32_dpp v24, v22 row_half_mirror row_mask:0xf bank_mask:0xf
	v_cmp_class_f32_e64 s[4:5], v20, v183
	v_fma_f32 v187, v78, v143, -v34
	v_fma_f32 v93, v62, v143, -v32
	v_cndmask_b32_e64 v20, v21, v20, s[4:5]
	s_waitcnt lgkmcnt(0)
	v_add_f32_e32 v22, v22, v24
	s_nop 1
	v_mov_b32_dpp v24, v22 row_mirror row_mask:0xf bank_mask:0xf
	v_mul_f32_e32 v26, v187, v187
	s_waitcnt lgkmcnt(0)
	v_add_f32_e32 v19, v22, v24
	v_mov_b32_e32 v22, v19
	s_nop 1
	v_permlane16_swap_b32_e32 v22, v19
	v_fmac_f32_e32 v26, v93, v93
	v_fma_f32 v167, v46, v143, -v36
	v_fmac_f32_e32 v26, v167, v167
	v_fma_f32 v143, v30, v143, -v48
	s_waitcnt lgkmcnt(0)
	v_add_f32_e32 v19, v19, v22
	v_fmamk_f32 v19, v19, 0x3c000000, v182
	v_mul_f32_e32 v22, 0x4f800000, v19
	v_cmp_gt_f32_e64 s[4:5], s87, v19
	v_fmac_f32_e32 v26, v143, v143
	s_nop 0
	v_cndmask_b32_e64 v19, v19, v22, s[4:5]
	v_sqrt_f32_e32 v22, v19
	s_nop 1
	v_mov_b32_dpp v27, v26 quad_perm:[1,0,3,2] row_mask:0xf bank_mask:0xf
	v_add_u32_e32 v21, -1, v22
	v_fma_f32 v24, -v21, v22, v19
	s_waitcnt lgkmcnt(0)
	v_add_f32_e32 v26, v26, v27
	v_cmp_ge_f32_e64 s[6:7], 0, v24
	v_add_u32_e32 v24, 1, v22
	s_nop 1
	v_mov_b32_dpp v27, v26 quad_perm:[2,3,0,1] row_mask:0xf bank_mask:0xf
	v_cndmask_b32_e64 v21, v22, v21, s[6:7]
	v_fma_f32 v22, -v24, v22, v19
	v_cmp_lt_f32_e64 s[6:7], 0, v22
	v_rcp_f32_e32 v150, v20
	s_nop 0
	v_mul_f32_e32 v150, s88, v150
	v_cndmask_b32_e64 v21, v21, v24, s[6:7]
	v_mul_f32_e32 v22, 0x37800000, v21
	v_cndmask_b32_e64 v21, v21, v22, s[4:5]
	s_waitcnt lgkmcnt(0)
	v_add_f32_e32 v22, v26, v27
	s_nop 1
	v_mov_b32_dpp v24, v22 row_half_mirror row_mask:0xf bank_mask:0xf
	v_cmp_class_f32_e64 s[4:5], v19, v183
	v_fma_f32 v188, v79, v147, -v35
	v_fma_f32 v94, v63, v147, -v33
	v_cndmask_b32_e64 v19, v21, v19, s[4:5]
	s_waitcnt lgkmcnt(0)
	v_add_f32_e32 v22, v22, v24
	s_nop 1
	v_mov_b32_dpp v24, v22 row_mirror row_mask:0xf bank_mask:0xf
	v_mul_f32_e32 v25, v188, v188
	s_waitcnt lgkmcnt(0)
	v_add_f32_e32 v20, v22, v24
	v_mov_b32_e32 v22, v20
	s_nop 1
	v_permlane16_swap_b32_e32 v22, v20
	v_fmac_f32_e32 v25, v94, v94
	v_fma_f32 v168, v47, v147, -v37
	v_fmac_f32_e32 v25, v168, v168
	v_fma_f32 v147, v31, v147, -v49
	s_waitcnt lgkmcnt(0)
	v_add_f32_e32 v20, v20, v22
	v_fmamk_f32 v20, v20, 0x3c000000, v182
	v_mul_f32_e32 v22, 0x4f800000, v20
	v_cmp_gt_f32_e64 s[4:5], s87, v20
	v_fmac_f32_e32 v25, v147, v147
	s_nop 0
	v_cndmask_b32_e64 v20, v20, v22, s[4:5]
	v_sqrt_f32_e32 v22, v20
	s_nop 1
	v_mov_b32_dpp v27, v25 quad_perm:[1,0,3,2] row_mask:0xf bank_mask:0xf
	v_add_u32_e32 v21, -1, v22
	v_fma_f32 v24, -v21, v22, v20
	s_waitcnt lgkmcnt(0)
	v_add_f32_e32 v25, v25, v27
	v_cmp_ge_f32_e64 s[6:7], 0, v24
	v_add_u32_e32 v24, 1, v22
	s_nop 1
	v_mov_b32_dpp v27, v25 quad_perm:[2,3,0,1] row_mask:0xf bank_mask:0xf
	v_cndmask_b32_e64 v21, v22, v21, s[6:7]
	v_fma_f32 v22, -v24, v22, v20
	v_cmp_lt_f32_e64 s[6:7], 0, v22
	v_rcp_f32_e32 v153, v19
	s_nop 0
	v_mul_f32_e32 v153, s88, v153
	v_cndmask_b32_e64 v21, v21, v24, s[6:7]
	v_mul_f32_e32 v22, 0x37800000, v21
	v_cndmask_b32_e64 v21, v21, v22, s[4:5]
	s_waitcnt lgkmcnt(0)
	v_add_f32_e32 v22, v25, v27
	s_nop 1
	v_mov_b32_dpp v24, v22 row_half_mirror row_mask:0xf bank_mask:0xf
	v_cmp_class_f32_e64 s[4:5], v20, v183
	v_mul_f32_e32 v46, 0xbfb8aa3b, v177
	v_exp_f32_e32 v50, v46
	v_cndmask_b32_e64 v20, v21, v20, s[4:5]
	s_waitcnt lgkmcnt(0)
	v_add_f32_e32 v22, v22, v24
	s_nop 1
	v_mov_b32_dpp v24, v22 row_mirror row_mask:0xf bank_mask:0xf
	v_lshl_add_u64 v[48:49], v[96:97], 0, s[44:45]
	v_or_b32_e32 v30, 0xa000, v174
	s_waitcnt lgkmcnt(0)
	v_add_f32_e32 v18, v22, v24
	v_mov_b32_e32 v19, v18
	s_nop 1
	v_permlane16_swap_b32_e32 v19, v18
	s_waitcnt lgkmcnt(0)
; __device__ __forceinline__ int crow(int r, int hi) { return (r & 3) + 8 * (r >> 2) + 4 * hi; }
; __device__ __forceinline__ float bf2f(bf16_t v) { return __uint_as_float((unsigned)v << 16); }
; __device__ __forceinline__ bf16_t f2bf(float f) { return (bf16_t)(cvtpk(f, 0.f) & 0xffffu); }
; template <int MODE>
; __device__ __forceinline__ void attn_unit(const Tensors& T0, int ureq, int b, int hh, int qblk, LAS3 char* shm, const bool dummy = false) {
;     ...
;       float ss[16];
; #pragma unroll
;       for (int r = 0; r < 16; ++r) { float s = 0.f;
; #pragma unroll
;         for (int d = 0; d < ND; ++d) { const float v = o[d][r] * rli[r] - X[(d * 16 + r) * 64 + lane]; o[d][r] = v; s += v * v; }
;         s += __shfl_xor(s, 1); s += __shfl_xor(s, 2); s += __shfl_xor(s, 4); s += __shfl_xor(s, 8); s += __shfl_xor(s, 16);
;         ss[r] = 0.8f / sqrtf(s * (1.0f / 128.0f) + 1e-6f); }
; #pragma unroll
;       for (int d = 0; d < ND; ++d) { const float gsub = T.subg[d * 32 + r32];
;         if (d + 1 < ND) {
; #pragma unroll
;           for (int r = 0; r < 16; ++r) gv[(d + 1) & 1][r] = gpb[(size_t)crow(r, hi) * 2048 + (d + 1) * 32]; }
; #pragma unroll
;         for (int r = 0; r < 16; ++r) { const float g = bf2f(gv[d & 1][r]); const float sg = g / (1.0f + __expf(-g));
;           gpb[(size_t)crow(r, hi) * 2048 + d * 32] = f2bf(o[d][r] * ss[r] * gsub * sg); } }
	v_add_f32_e32 v18, v18, v19
	v_fmamk_f32 v18, v18, 0x3c000000, v182
	v_mul_f32_e32 v19, 0x4f800000, v18
	v_cmp_gt_f32_e64 s[4:5], s87, v18
	s_nop 1
	v_cndmask_b32_e64 v18, v18, v19, s[4:5]
	v_sqrt_f32_e32 v19, v18
	v_rcp_f32_e32 v156, v20
	s_nop 0
	v_mul_f32_e32 v156, s88, v156
	v_mov_b32_e32 v31, v175
	v_add_u32_e32 v22, -1, v19
	v_fma_f32 v23, -v22, v19, v18
	v_cmp_ge_f32_e32 vcc, 0, v23
	v_add_u32_e32 v23, 1, v19
	v_mov_b32_e32 v21, v175
	v_cndmask_b32_e32 v22, v19, v22, vcc
	v_fma_f32 v19, -v23, v19, v18
	v_cmp_lt_f32_e32 vcc, 0, v19
	v_lshl_add_u64 v[66:67], v[48:49], 0, v[30:31]
	v_or_b32_e32 v32, 0xb000, v174
	v_cndmask_b32_e32 v19, v22, v23, vcc
	v_mul_f32_e32 v22, 0x37800000, v19
	v_cndmask_b32_e64 v19, v19, v22, s[4:5]
	v_cmp_class_f32_e32 vcc, v18, v183
	v_mov_b32_e32 v33, v175
	v_or_b32_e32 v34, 0x10000, v174
	v_cndmask_b32_e32 v22, v19, v18, vcc
	v_lshlrev_b32_e32 v18, 2, v186
	v_mov_b32_e32 v19, v175
	v_lshl_add_u64 v[78:79], s[48:49], 0, v[18:19]
	global_load_dword v95, v[78:79], off
	v_add_f32_e32 v186, 1.0, v50
	v_rcp_f32_e32 v190, v186
	s_nop 0
	v_mul_f32_e32 v190, v177, v190
	v_mul_f32_e32 v191, v189, v117
	global_load_dword v186, v[78:79], off offset:128
	global_load_dword v189, v[78:79], off offset:256
	global_load_dword v177, v[78:79], off offset:384
	v_mul_f32_e32 v79, 0xbfb8aa3b, v125
	v_exp_f32_e32 v79, v79
	v_rcp_f32_e32 v155, v22
	s_nop 0
	v_mul_f32_e32 v155, s88, v155
	v_lshl_add_u64 v[18:19], v[96:97], 0, v[174:175]
	v_or_b32_e32 v20, 0x1000, v174
	v_add_f32_e32 v79, 1.0, v79
	v_or_b32_e32 v22, 0x2000, v174
	v_mov_b32_e32 v23, v175
	v_mov_b32_e32 v35, v175
	v_or_b32_e32 v38, 0x11000, v174
	v_mov_b32_e32 v39, v175
	v_or_b32_e32 v36, 0x12000, v174
	v_mov_b32_e32 v37, v175
	v_or_b32_e32 v40, 0x13000, v174
	v_mov_b32_e32 v41, v175
	v_or_b32_e32 v44, 0x18000, v174
	v_mov_b32_e32 v45, v175
	v_or_b32_e32 v42, 0x19000, v174
	v_mov_b32_e32 v43, v175
	v_lshl_add_u64 v[76:77], v[48:49], 0, v[20:21]
	v_lshl_add_u64 v[74:75], v[48:49], 0, v[22:23]
	v_lshl_add_u64 v[64:65], v[48:49], 0, v[32:33]
	v_lshl_add_u64 v[62:63], v[48:49], 0, v[34:35]
	v_lshl_add_u64 v[60:61], v[48:49], 0, v[38:39]
	v_lshl_add_u64 v[58:59], v[48:49], 0, v[36:37]
	v_lshl_add_u64 v[56:57], v[48:49], 0, v[40:41]
	v_lshl_add_u64 v[54:55], v[48:49], 0, v[44:45]
	v_lshl_add_u64 v[52:53], v[48:49], 0, v[42:43]
	global_load_ushort v193, v[18:19], off offset:2112
	global_load_ushort v195, v[76:77], off
	global_load_ushort v200, v[74:75], off
	v_or_b32_e32 v24, 0x3000, v174
	v_mov_b32_e32 v25, v175
	v_or_b32_e32 v26, 0x8000, v174
	v_mov_b32_e32 v27, v175
	v_or_b32_e32 v28, 0x9000, v174
	v_mov_b32_e32 v29, v175
	v_or_b32_e32 v46, 0x1a000, v174
	v_mov_b32_e32 v47, v175
	v_or_b32_e32 v174, 0x1b000, v174
	v_lshl_add_u64 v[72:73], v[48:49], 0, v[24:25]
	v_lshl_add_u64 v[70:71], v[48:49], 0, v[26:27]
	v_lshl_add_u64 v[68:69], v[48:49], 0, v[28:29]
	v_lshl_add_u64 v[50:51], v[48:49], 0, v[46:47]
	v_lshl_add_u64 v[48:49], v[48:49], 0, v[174:175]
	s_waitcnt lgkmcnt(0)
	s_waitcnt vmcnt(6)
	v_mul_f32_e32 v78, v191, v95
	v_mul_f32_e32 v78, v190, v78
	v_cvt_pk_bf16_f32 v78, v78, s0
	global_load_ushort v201, v[66:67], off
	global_load_ushort v202, v[64:65], off
	global_load_ushort v198, v[62:63], off
	global_load_ushort v196, v[60:61], off
	global_load_ushort v194, v[58:59], off
	global_load_ushort v192, v[56:57], off
	global_load_ushort v191, v[54:55], off
	global_load_ushort v190, v[52:53], off
	v_mul_f32_e32 v80, v80, v95
	global_store_short v[18:19], v78, off offset:2048
	v_rcp_f32_e32 v78, v79
	s_nop 0
	v_mul_f32_e32 v78, v125, v78
	v_mul_f32_e32 v79, 0xbfb8aa3b, v123
	v_exp_f32_e32 v79, v79
	v_mul_f32_e32 v78, v78, v80
	v_cvt_pk_bf16_f32 v199, v78, s0
	v_add_f32_e32 v80, 1.0, v79
	v_lshl_add_u64 v[78:79], v[16:17], 0, v[20:21]
	global_store_short v[78:79], v199, off
	v_mul_f32_e32 v79, 0xbfb8aa3b, v121
	v_exp_f32_e32 v79, v79
	v_rcp_f32_e32 v78, v80
	s_nop 0
	v_mul_f32_e32 v78, v123, v78
	v_mul_f32_e32 v80, v81, v119
	v_mul_f32_e32 v80, v80, v95
	v_mul_f32_e32 v78, v78, v80
	v_add_f32_e32 v80, 1.0, v79
	v_cvt_pk_bf16_f32 v125, v78, s0
	v_lshl_add_u64 v[78:79], v[16:17], 0, v[22:23]
	global_store_short v[78:79], v125, off
	v_mul_f32_e32 v79, 0xbfb8aa3b, v109
	v_exp_f32_e32 v79, v79
	v_rcp_f32_e32 v78, v80
	s_nop 0
	v_mul_f32_e32 v78, v121, v78
	v_mul_f32_e32 v80, v82, v122
	v_mul_f32_e32 v80, v80, v95
	v_mul_f32_e32 v78, v78, v80
	v_add_f32_e32 v80, 1.0, v79
	v_cvt_pk_bf16_f32 v121, v78, s0
	v_lshl_add_u64 v[78:79], v[16:17], 0, v[24:25]
	global_store_short v[78:79], v121, off
	v_mul_f32_e32 v79, 0xbfb8aa3b, v108
	v_exp_f32_e32 v79, v79
	v_rcp_f32_e32 v78, v80
	s_nop 0
	v_mul_f32_e32 v78, v109, v78
	v_mul_f32_e32 v80, v83, v124
	v_mul_f32_e32 v80, v80, v95
	v_mul_f32_e32 v78, v78, v80
	v_add_f32_e32 v80, 1.0, v79
	v_cvt_pk_bf16_f32 v83, v78, s0
	v_lshl_add_u64 v[78:79], v[16:17], 0, v[26:27]
	global_store_short v[78:79], v83, off
	v_mul_f32_e32 v79, 0xbfb8aa3b, v107
	v_exp_f32_e32 v79, v79
	v_rcp_f32_e32 v78, v80
	s_nop 0
	v_mul_f32_e32 v78, v108, v78
	v_mul_f32_e32 v80, v84, v126
	v_mul_f32_e32 v80, v80, v95
	v_mul_f32_e32 v78, v78, v80
	v_add_f32_e32 v80, 1.0, v79
	v_cvt_pk_bf16_f32 v83, v78, s0
	v_lshl_add_u64 v[78:79], v[16:17], 0, v[28:29]
	global_store_short v[78:79], v83, off
	v_mul_f32_e32 v79, 0xbfb8aa3b, v106
	v_exp_f32_e32 v79, v79
	v_rcp_f32_e32 v78, v80
	s_nop 0
	v_mul_f32_e32 v78, v107, v78
	v_mul_f32_e32 v80, v85, v140
	v_mul_f32_e32 v80, v80, v95
	v_mul_f32_e32 v78, v78, v80
	v_add_f32_e32 v80, 1.0, v79
	v_cvt_pk_bf16_f32 v83, v78, s0
	v_lshl_add_u64 v[78:79], v[16:17], 0, v[30:31]
	global_store_short v[78:79], v83, off
	v_mul_f32_e32 v79, 0xbfb8aa3b, v105
; __device__ __forceinline__ int crow(int r, int hi) { return (r & 3) + 8 * (r >> 2) + 4 * hi; }
; __device__ __forceinline__ float bf2f(bf16_t v) { return __uint_as_float((unsigned)v << 16); }
; __device__ __forceinline__ bf16_t f2bf(float f) { return (bf16_t)(cvtpk(f, 0.f) & 0xffffu); }
; template <int MODE>
; __device__ __forceinline__ void attn_unit(const Tensors& T0, int ureq, int b, int hh, int qblk, LAS3 char* shm, const bool dummy = false) {
;     ...
; #pragma unroll
;       for (int d = 0; d < ND; ++d) { const float gsub = T.subg[d * 32 + r32];
;         if (d + 1 < ND) {
; #pragma unroll
;           for (int r = 0; r < 16; ++r) gv[(d + 1) & 1][r] = gpb[(size_t)crow(r, hi) * 2048 + (d + 1) * 32]; }
; #pragma unroll
;         for (int r = 0; r < 16; ++r) { const float g = bf2f(gv[d & 1][r]); const float sg = g / (1.0f + __expf(-g));
;           gpb[(size_t)crow(r, hi) * 2048 + d * 32] = f2bf(o[d][r] * ss[r] * gsub * sg); } }
	v_exp_f32_e32 v79, v79
	v_rcp_f32_e32 v78, v80
	s_nop 0
	v_mul_f32_e32 v78, v106, v78
	v_mul_f32_e32 v80, v86, v142
	v_mul_f32_e32 v80, v80, v95
	v_mul_f32_e32 v78, v78, v80
	v_add_f32_e32 v80, 1.0, v79
	v_cvt_pk_bf16_f32 v83, v78, s0
	v_lshl_add_u64 v[78:79], v[16:17], 0, v[32:33]
	global_store_short v[78:79], v83, off
	v_mul_f32_e32 v79, 0xbfb8aa3b, v104
	v_exp_f32_e32 v79, v79
	v_rcp_f32_e32 v78, v80
	s_nop 0
	v_mul_f32_e32 v78, v105, v78
	v_mul_f32_e32 v80, v87, v144
	v_mul_f32_e32 v80, v80, v95
	v_mul_f32_e32 v78, v78, v80
	v_add_f32_e32 v80, 1.0, v79
	v_cvt_pk_bf16_f32 v83, v78, s0
	v_lshl_add_u64 v[78:79], v[16:17], 0, v[34:35]
	global_store_short v[78:79], v83, off
	v_mul_f32_e32 v79, 0xbfb8aa3b, v103
	v_exp_f32_e32 v79, v79
	v_rcp_f32_e32 v78, v80
	s_nop 0
	v_mul_f32_e32 v78, v104, v78
	v_mul_f32_e32 v80, v88, v145
	v_mul_f32_e32 v80, v80, v95
	v_mul_f32_e32 v78, v78, v80
	v_add_f32_e32 v80, 1.0, v79
	v_cvt_pk_bf16_f32 v83, v78, s0
	v_lshl_add_u64 v[78:79], v[16:17], 0, v[38:39]
	global_store_short v[78:79], v83, off
	v_mul_f32_e32 v79, 0xbfb8aa3b, v102
	v_exp_f32_e32 v79, v79
	v_rcp_f32_e32 v78, v80
	s_nop 0
	v_mul_f32_e32 v78, v103, v78
	v_mul_f32_e32 v80, v89, v146
	v_mul_f32_e32 v80, v80, v95
	v_mul_f32_e32 v78, v78, v80
	v_add_f32_e32 v80, 1.0, v79
	v_cvt_pk_bf16_f32 v83, v78, s0
	v_lshl_add_u64 v[78:79], v[16:17], 0, v[36:37]
	global_store_short v[78:79], v83, off
	v_mul_f32_e32 v79, 0xbfb8aa3b, v101
	v_exp_f32_e32 v79, v79
	v_rcp_f32_e32 v78, v80
	s_nop 0
	v_mul_f32_e32 v78, v102, v78
	v_mul_f32_e32 v80, v90, v148
	v_mul_f32_e32 v80, v80, v95
	v_mul_f32_e32 v78, v78, v80
	v_add_f32_e32 v80, 1.0, v79
	v_cvt_pk_bf16_f32 v83, v78, s0
	v_lshl_add_u64 v[78:79], v[16:17], 0, v[40:41]
	global_store_short v[78:79], v83, off
	v_mul_f32_e32 v79, 0xbfb8aa3b, v100
	v_exp_f32_e32 v79, v79
	v_rcp_f32_e32 v78, v80
	s_nop 0
	v_mul_f32_e32 v78, v101, v78
	v_mul_f32_e32 v80, v91, v150
	v_mul_f32_e32 v80, v80, v95
	v_mul_f32_e32 v78, v78, v80
	v_add_f32_e32 v80, 1.0, v79
	v_cvt_pk_bf16_f32 v83, v78, s0
	v_lshl_add_u64 v[78:79], v[16:17], 0, v[44:45]
	global_store_short v[78:79], v83, off
	v_mul_f32_e32 v79, 0xbfb8aa3b, v99
	v_exp_f32_e32 v79, v79
	v_rcp_f32_e32 v78, v80
	s_nop 0
	v_mul_f32_e32 v78, v100, v78
	v_mul_f32_e32 v80, v92, v153
	v_mul_f32_e32 v80, v80, v95
	v_mul_f32_e32 v78, v78, v80
	v_add_f32_e32 v80, 1.0, v79
	v_cvt_pk_bf16_f32 v83, v78, s0
	v_lshl_add_u64 v[78:79], v[16:17], 0, v[42:43]
	global_store_short v[78:79], v83, off
	v_mul_f32_e32 v79, 0xbfb8aa3b, v98
	v_exp_f32_e32 v79, v79
	v_rcp_f32_e32 v78, v80
	s_nop 0
	v_mul_f32_e32 v78, v99, v78
	v_mul_f32_e32 v80, v93, v156
	v_mul_f32_e32 v80, v80, v95
	v_mul_f32_e32 v78, v78, v80
	v_add_f32_e32 v80, 1.0, v79
	v_cvt_pk_bf16_f32 v83, v78, s0
	v_lshl_add_u64 v[78:79], v[16:17], 0, v[46:47]
	global_store_short v[78:79], v83, off
	v_mul_f32_e32 v79, v94, v155
	v_rcp_f32_e32 v78, v80
	s_nop 0
	v_mul_f32_e32 v78, v98, v78
	v_mul_f32_e32 v79, v95, v79
	v_mul_f32_e32 v78, v78, v79
	v_cvt_pk_bf16_f32 v78, v78, s0
	v_lshl_add_u64 v[16:17], v[16:17], 0, v[174:175]
	global_store_short v[16:17], v78, off
	global_load_ushort v203, v[72:73], off
	global_load_ushort v204, v[70:71], off
	global_load_ushort v205, v[68:69], off
	global_load_ushort v206, v[18:19], off offset:2176
	global_load_ushort v121, v[18:19], off offset:2240
	s_waitcnt vmcnt(31)
	v_lshlrev_b32_e32 v123, 16, v193
	v_mul_f32_e32 v78, 0xbfb8aa3b, v123
	v_exp_f32_e32 v78, v78
	v_lshl_add_u64 v[16:17], v[96:97], 0, s[66:67]
	v_lshl_add_u64 v[108:109], v[16:17], 0, v[20:21]
	v_lshl_add_u64 v[106:107], v[16:17], 0, v[22:23]
	v_add_f32_e32 v125, 1.0, v78
	v_lshl_add_u64 v[104:105], v[16:17], 0, v[24:25]
	v_lshl_add_u64 v[102:103], v[16:17], 0, v[26:27]
	v_lshl_add_u64 v[100:101], v[16:17], 0, v[28:29]
	v_lshl_add_u64 v[98:99], v[16:17], 0, v[30:31]
	v_lshl_add_u64 v[94:95], v[16:17], 0, v[32:33]
	v_lshl_add_u64 v[92:93], v[16:17], 0, v[34:35]
	v_lshl_add_u64 v[90:91], v[16:17], 0, v[38:39]
	v_lshl_add_u64 v[88:89], v[16:17], 0, v[36:37]
	v_lshl_add_u64 v[86:87], v[16:17], 0, v[40:41]
	v_lshl_add_u64 v[84:85], v[16:17], 0, v[44:45]
	v_lshl_add_u64 v[82:83], v[16:17], 0, v[42:43]
	v_lshl_add_u64 v[80:81], v[16:17], 0, v[46:47]
	v_lshl_add_u64 v[78:79], v[16:17], 0, v[174:175]
	v_mul_f32_e32 v17, v149, v117
	v_rcp_f32_e32 v16, v125
	s_nop 0
	v_mul_f32_e32 v16, v123, v16
	v_mul_f32_e32 v17, v17, v186
	v_mul_f32_e32 v16, v16, v17
	s_waitcnt vmcnt(30)
	v_lshlrev_b32_e32 v17, 16, v195
	v_mul_f32_e32 v123, 0xbfb8aa3b, v17
	v_exp_f32_e32 v123, v123
	v_cvt_pk_bf16_f32 v16, v16, s0
	global_load_ushort v207, v[50:51], off
	global_load_ushort v208, v[48:49], off
	global_load_ushort v209, v[108:109], off
	global_load_ushort v210, v[106:107], off
	global_load_ushort v211, v[104:105], off
	global_load_ushort v212, v[102:103], off
	global_load_ushort v213, v[100:101], off
	global_load_ushort v214, v[98:99], off
	s_waitcnt vmcnt(37)
	v_lshlrev_b32_e32 v200, 16, v200
	v_add_f32_e32 v215, 1.0, v123
	global_load_ushort v218, v[94:95], off
	global_load_ushort v199, v[92:93], off
	global_load_ushort v197, v[90:91], off
	global_load_ushort v195, v[88:89], off
	global_load_ushort v193, v[86:87], off
	global_load_ushort v149, v[84:85], off
	global_load_ushort v125, v[82:83], off
	global_load_ushort v123, v[80:81], off
	s_nop 0
	global_store_short v[18:19], v16, off offset:2112
	v_mul_f32_e32 v216, 0xbfb8aa3b, v200
	v_exp_f32_e32 v216, v216
	v_rcp_f32_e32 v16, v215
	s_nop 0
	v_mul_f32_e32 v16, v17, v16
	v_mul_f32_e32 v17, v151, v118
	v_add_f32_e32 v151, 1.0, v216
	v_mul_f32_e32 v17, v17, v186
	v_mul_f32_e32 v16, v16, v17
	v_cvt_pk_bf16_f32 v16, v16, s0
	global_store_short v[76:77], v16, off
	s_waitcnt lgkmcnt(0)
; __device__ __forceinline__ int crow(int r, int hi) { return (r & 3) + 8 * (r >> 2) + 4 * hi; }
; __device__ __forceinline__ float bf2f(bf16_t v) { return __uint_as_float((unsigned)v << 16); }
; __device__ __forceinline__ bf16_t f2bf(float f) { return (bf16_t)(cvtpk(f, 0.f) & 0xffffu); }
; template <int MODE>
; __device__ __forceinline__ void attn_unit(const Tensors& T0, int ureq, int b, int hh, int qblk, LAS3 char* shm, const bool dummy = false) {
;     ...
; #pragma unroll
;       for (int d = 0; d < ND; ++d) { const float gsub = T.subg[d * 32 + r32];
;         if (d + 1 < ND) {
; #pragma unroll
;           for (int r = 0; r < 16; ++r) gv[(d + 1) & 1][r] = gpb[(size_t)crow(r, hi) * 2048 + (d + 1) * 32]; }
; #pragma unroll
;         for (int r = 0; r < 16; ++r) { const float g = bf2f(gv[d & 1][r]); const float sg = g / (1.0f + __expf(-g));
;           gpb[(size_t)crow(r, hi) * 2048 + d * 32] = f2bf(o[d][r] * ss[r] * gsub * sg); } }
	s_waitcnt vmcnt(22)
	v_lshlrev_b32_e32 v17, 16, v203
	v_mul_f32_e32 v76, 0xbfb8aa3b, v17
	v_exp_f32_e32 v76, v76
	v_rcp_f32_e32 v16, v151
	s_nop 0
	v_mul_f32_e32 v16, v200, v16
	v_mul_f32_e32 v77, v152, v119
	v_mul_f32_e32 v77, v77, v186
	v_add_f32_e32 v76, 1.0, v76
	v_mul_f32_e32 v16, v16, v77
	v_cvt_pk_bf16_f32 v16, v16, s0
	global_store_short v[74:75], v16, off
	s_waitcnt vmcnt(22)
	v_lshlrev_b32_e32 v74, 16, v204
	v_mul_f32_e32 v75, 0xbfb8aa3b, v74
	v_exp_f32_e32 v75, v75
	v_rcp_f32_e32 v16, v76
	s_nop 0
	v_mul_f32_e32 v16, v17, v16
	v_mul_f32_e32 v17, v154, v122
	v_mul_f32_e32 v17, v17, v186
	v_add_f32_e32 v75, 1.0, v75
	v_mul_f32_e32 v16, v16, v17
	v_cvt_pk_bf16_f32 v16, v16, s0
	global_store_short v[72:73], v16, off
	s_waitcnt vmcnt(22)
	v_lshlrev_b32_e32 v17, 16, v205
	v_mul_f32_e32 v72, 0xbfb8aa3b, v17
	v_exp_f32_e32 v72, v72
	v_rcp_f32_e32 v16, v75
	s_nop 0
	v_mul_f32_e32 v16, v74, v16
	v_mul_f32_e32 v73, v157, v124
	v_mul_f32_e32 v73, v73, v186
	v_add_f32_e32 v72, 1.0, v72
	v_mul_f32_e32 v16, v16, v73
	v_cvt_pk_bf16_f32 v16, v16, s0
	global_store_short v[70:71], v16, off
	v_lshlrev_b32_e32 v70, 16, v201
	v_mul_f32_e32 v71, 0xbfb8aa3b, v70
	v_exp_f32_e32 v71, v71
	v_rcp_f32_e32 v16, v72
	s_nop 0
	v_mul_f32_e32 v16, v17, v16
	v_mul_f32_e32 v17, v158, v126
	v_mul_f32_e32 v17, v17, v186
	v_add_f32_e32 v71, 1.0, v71
	v_mul_f32_e32 v16, v16, v17
	v_cvt_pk_bf16_f32 v16, v16, s0
	global_store_short v[68:69], v16, off
	v_lshlrev_b32_e32 v17, 16, v202
	v_mul_f32_e32 v68, 0xbfb8aa3b, v17
	v_exp_f32_e32 v68, v68
	v_rcp_f32_e32 v16, v71
	s_nop 0
	v_mul_f32_e32 v16, v70, v16
	v_mul_f32_e32 v69, v159, v140
	v_mul_f32_e32 v69, v69, v186
	v_add_f32_e32 v68, 1.0, v68
	v_mul_f32_e32 v16, v16, v69
	v_cvt_pk_bf16_f32 v16, v16, s0
	global_store_short v[66:67], v16, off
	v_lshlrev_b32_e32 v66, 16, v198
	v_mul_f32_e32 v67, 0xbfb8aa3b, v66
	v_exp_f32_e32 v67, v67
	v_rcp_f32_e32 v16, v68
	s_nop 0
	v_mul_f32_e32 v16, v17, v16
	v_mul_f32_e32 v17, v160, v142
	v_mul_f32_e32 v17, v17, v186
	v_add_f32_e32 v67, 1.0, v67
	v_mul_f32_e32 v16, v16, v17
	v_cvt_pk_bf16_f32 v16, v16, s0
	global_store_short v[64:65], v16, off
	v_lshlrev_b32_e32 v17, 16, v196
	v_mul_f32_e32 v64, 0xbfb8aa3b, v17
	v_exp_f32_e32 v64, v64
	v_rcp_f32_e32 v16, v67
	s_nop 0
	v_mul_f32_e32 v16, v66, v16
	v_mul_f32_e32 v65, v169, v144
	v_mul_f32_e32 v65, v65, v186
	v_add_f32_e32 v64, 1.0, v64
	v_mul_f32_e32 v16, v16, v65
	v_cvt_pk_bf16_f32 v16, v16, s0
	global_store_short v[62:63], v16, off
	v_lshlrev_b32_e32 v62, 16, v194
	v_mul_f32_e32 v63, 0xbfb8aa3b, v62
	v_exp_f32_e32 v63, v63
	v_rcp_f32_e32 v16, v64
	s_nop 0
	v_mul_f32_e32 v16, v17, v16
	v_mul_f32_e32 v17, v170, v145
	v_mul_f32_e32 v17, v17, v186
	v_add_f32_e32 v63, 1.0, v63
	v_mul_f32_e32 v16, v16, v17
	v_cvt_pk_bf16_f32 v16, v16, s0
	global_store_short v[60:61], v16, off
	v_lshlrev_b32_e32 v17, 16, v192
	v_mul_f32_e32 v60, 0xbfb8aa3b, v17
	v_exp_f32_e32 v60, v60
	v_rcp_f32_e32 v16, v63
	s_nop 0
	v_mul_f32_e32 v16, v62, v16
	v_mul_f32_e32 v61, v171, v146
	v_mul_f32_e32 v61, v61, v186
	v_add_f32_e32 v60, 1.0, v60
	v_mul_f32_e32 v16, v16, v61
	v_cvt_pk_bf16_f32 v16, v16, s0
	global_store_short v[58:59], v16, off
	v_lshlrev_b32_e32 v58, 16, v191
	v_mul_f32_e32 v59, 0xbfb8aa3b, v58
	v_exp_f32_e32 v59, v59
	v_rcp_f32_e32 v16, v60
	s_nop 0
	v_mul_f32_e32 v16, v17, v16
	v_mul_f32_e32 v17, v176, v148
	v_mul_f32_e32 v17, v17, v186
	v_add_f32_e32 v59, 1.0, v59
	v_mul_f32_e32 v16, v16, v17
	v_cvt_pk_bf16_f32 v16, v16, s0
	global_store_short v[56:57], v16, off
	v_lshlrev_b32_e32 v17, 16, v190
	v_mul_f32_e32 v56, 0xbfb8aa3b, v17
	v_exp_f32_e32 v56, v56
	v_rcp_f32_e32 v16, v59
	s_nop 0
	v_mul_f32_e32 v16, v58, v16
	v_mul_f32_e32 v57, v178, v150
	v_mul_f32_e32 v57, v57, v186
	v_add_f32_e32 v56, 1.0, v56
	v_mul_f32_e32 v16, v16, v57
	v_cvt_pk_bf16_f32 v16, v16, s0
	global_store_short v[54:55], v16, off
	s_waitcnt vmcnt(28)
	v_lshlrev_b32_e32 v54, 16, v207
	v_mul_f32_e32 v55, 0xbfb8aa3b, v54
	v_exp_f32_e32 v55, v55
	v_rcp_f32_e32 v16, v56
	s_nop 0
	v_mul_f32_e32 v16, v17, v16
	v_mul_f32_e32 v17, v179, v153
	v_mul_f32_e32 v17, v17, v186
	v_add_f32_e32 v55, 1.0, v55
	v_mul_f32_e32 v16, v16, v17
	v_cvt_pk_bf16_f32 v16, v16, s0
	global_store_short v[52:53], v16, off
	s_waitcnt vmcnt(28)
	v_lshlrev_b32_e32 v17, 16, v208
	v_mul_f32_e32 v52, 0xbfb8aa3b, v17
	v_exp_f32_e32 v52, v52
	v_rcp_f32_e32 v16, v55
	s_nop 0
	v_mul_f32_e32 v16, v54, v16
	v_mul_f32_e32 v53, v187, v156
	v_mul_f32_e32 v53, v53, v186
	v_add_f32_e32 v52, 1.0, v52
	v_mul_f32_e32 v16, v16, v53
	v_cvt_pk_bf16_f32 v16, v16, s0
	global_store_short v[50:51], v16, off
	v_rcp_f32_e32 v16, v52
	s_nop 0
	v_mul_f32_e32 v16, v17, v16
	v_mul_f32_e32 v17, v188, v155
	v_mul_f32_e32 v17, v17, v186
	v_mul_f32_e32 v16, v16, v17
	v_cvt_pk_bf16_f32 v16, v16, s0
	global_store_short v[48:49], v16, off
	v_lshl_add_u64 v[16:17], v[96:97], 0, s[46:47]
	v_lshl_add_u64 v[48:49], v[16:17], 0, v[32:33]
	v_lshl_add_u64 v[32:33], v[16:17], 0, v[34:35]
	v_lshlrev_b32_e32 v34, 16, v206
	v_lshl_add_u64 v[60:61], v[16:17], 0, v[20:21]
	v_mul_f32_e32 v20, 0xbfb8aa3b, v34
	v_exp_f32_e32 v20, v20
	v_lshl_add_u64 v[52:53], v[16:17], 0, v[28:29]
	v_lshl_add_u64 v[28:29], v[16:17], 0, v[36:37]
	v_lshl_add_u64 v[50:51], v[16:17], 0, v[30:31]
	v_add_f32_e32 v35, 1.0, v20
	v_lshl_add_u64 v[30:31], v[16:17], 0, v[38:39]
	v_lshl_add_u64 v[54:55], v[16:17], 0, v[26:27]
	v_lshl_add_u64 v[26:27], v[16:17], 0, v[40:41]
	v_rcp_f32_e32 v36, v35
	s_nop 0
	v_mul_f32_e32 v34, v34, v36
	v_mul_f32_e32 v35, v127, v117
	v_mul_f32_e32 v35, v35, v189
	v_lshl_add_u64 v[56:57], v[16:17], 0, v[24:25]
	v_lshl_add_u64 v[24:25], v[16:17], 0, v[44:45]
	v_mul_f32_e32 v34, v34, v35
	s_waitcnt vmcnt(29)
; __device__ __forceinline__ int crow(int r, int hi) { return (r & 3) + 8 * (r >> 2) + 4 * hi; }
; __device__ __forceinline__ float bf2f(bf16_t v) { return __uint_as_float((unsigned)v << 16); }
; __device__ __forceinline__ bf16_t f2bf(float f) { return (bf16_t)(cvtpk(f, 0.f) & 0xffffu); }
; template <int MODE>
; __device__ __forceinline__ void attn_unit(const Tensors& T0, int ureq, int b, int hh, int qblk, LAS3 char* shm, const bool dummy = false) {
;     ...
; #pragma unroll
;       for (int d = 0; d < ND; ++d) { const float gsub = T.subg[d * 32 + r32];
;         if (d + 1 < ND) {
; #pragma unroll
;           for (int r = 0; r < 16; ++r) gv[(d + 1) & 1][r] = gpb[(size_t)crow(r, hi) * 2048 + (d + 1) * 32]; }
; #pragma unroll
;         for (int r = 0; r < 16; ++r) { const float g = bf2f(gv[d & 1][r]); const float sg = g / (1.0f + __expf(-g));
;           gpb[(size_t)crow(r, hi) * 2048 + d * 32] = f2bf(o[d][r] * ss[r] * gsub * sg); } }
	v_lshlrev_b32_e32 v44, 16, v209
	v_lshl_add_u64 v[58:59], v[16:17], 0, v[22:23]
	v_lshl_add_u64 v[22:23], v[16:17], 0, v[42:43]
	v_cvt_pk_bf16_f32 v43, v34, s0
	v_mul_f32_e32 v34, 0xbfb8aa3b, v44
	v_exp_f32_e32 v34, v34
	v_lshl_add_u64 v[20:21], v[16:17], 0, v[46:47]
	v_lshl_add_u64 v[16:17], v[16:17], 0, v[174:175]
	global_load_ushort v45, v[78:79], off
	global_load_ushort v46, v[60:61], off
	global_load_ushort v47, v[58:59], off
	global_load_ushort v62, v[56:57], off
	global_load_ushort v63, v[54:55], off
	global_load_ushort v64, v[52:53], off
	global_load_ushort v65, v[50:51], off
	global_load_ushort v42, v[48:49], off
	v_add_f32_e32 v66, 1.0, v34
	global_load_ushort v41, v[32:33], off
	global_load_ushort v40, v[30:31], off
	global_load_ushort v39, v[28:29], off
	global_load_ushort v38, v[26:27], off
	global_load_ushort v37, v[24:25], off
	global_load_ushort v36, v[22:23], off
	global_load_ushort v35, v[20:21], off
	global_load_ushort v34, v[16:17], off
	s_waitcnt lgkmcnt(0)
	s_waitcnt vmcnt(6)
	v_lshlrev_b32_e32 v40, 16, v40
	global_store_short v[18:19], v43, off offset:2176
	v_lshlrev_b32_e32 v67, 16, v210
	v_mul_f32_e32 v68, 0xbfb8aa3b, v67
	v_exp_f32_e32 v68, v68
	v_rcp_f32_e32 v43, v66
	s_nop 0
	v_mul_f32_e32 v43, v44, v43
	v_mul_f32_e32 v44, v128, v118
	v_mul_f32_e32 v44, v44, v189
	v_add_f32_e32 v66, 1.0, v68
	v_mul_f32_e32 v43, v43, v44
	v_cvt_pk_bf16_f32 v43, v43, s0
	global_store_short v[108:109], v43, off
	v_lshlrev_b32_e32 v44, 16, v211
	v_mul_f32_e32 v68, 0xbfb8aa3b, v44
	v_exp_f32_e32 v68, v68
	v_rcp_f32_e32 v43, v66
	s_nop 0
	v_mul_f32_e32 v43, v67, v43
	v_mul_f32_e32 v66, v129, v119
	v_mul_f32_e32 v66, v66, v189
	v_add_f32_e32 v67, 1.0, v68
	v_mul_f32_e32 v43, v43, v66
	v_cvt_pk_bf16_f32 v43, v43, s0
	global_store_short v[106:107], v43, off
	v_lshlrev_b32_e32 v66, 16, v212
	v_mul_f32_e32 v68, 0xbfb8aa3b, v66
	v_exp_f32_e32 v68, v68
	v_rcp_f32_e32 v43, v67
	s_nop 0
	v_mul_f32_e32 v43, v44, v43
	v_mul_f32_e32 v44, v130, v122
	v_mul_f32_e32 v44, v44, v189
	v_add_f32_e32 v67, 1.0, v68
	v_mul_f32_e32 v43, v43, v44
	v_cvt_pk_bf16_f32 v43, v43, s0
	global_store_short v[104:105], v43, off
	v_lshlrev_b32_e32 v44, 16, v213
	v_mul_f32_e32 v68, 0xbfb8aa3b, v44
	v_exp_f32_e32 v68, v68
	v_rcp_f32_e32 v43, v67
	s_nop 0
	v_mul_f32_e32 v43, v66, v43
	v_mul_f32_e32 v66, v131, v124
	v_mul_f32_e32 v66, v66, v189
	v_add_f32_e32 v67, 1.0, v68
	v_mul_f32_e32 v43, v43, v66
	v_cvt_pk_bf16_f32 v43, v43, s0
	global_store_short v[102:103], v43, off
	v_lshlrev_b32_e32 v66, 16, v214
	v_mul_f32_e32 v68, 0xbfb8aa3b, v66
	v_exp_f32_e32 v68, v68
	v_rcp_f32_e32 v43, v67
	s_nop 0
	v_mul_f32_e32 v43, v44, v43
	v_mul_f32_e32 v44, v132, v126
	v_mul_f32_e32 v44, v44, v189
	v_add_f32_e32 v67, 1.0, v68
	v_mul_f32_e32 v43, v43, v44
	v_cvt_pk_bf16_f32 v43, v43, s0
	global_store_short v[100:101], v43, off
	v_lshlrev_b32_e32 v44, 16, v218
	v_mul_f32_e32 v68, 0xbfb8aa3b, v44
	v_exp_f32_e32 v68, v68
	v_rcp_f32_e32 v43, v67
	s_nop 0
	v_mul_f32_e32 v43, v66, v43
	v_mul_f32_e32 v66, v133, v140
	v_mul_f32_e32 v66, v66, v189
	v_add_f32_e32 v67, 1.0, v68
	v_mul_f32_e32 v43, v43, v66
	v_cvt_pk_bf16_f32 v43, v43, s0
	global_store_short v[98:99], v43, off
	v_lshlrev_b32_e32 v66, 16, v199
	v_mul_f32_e32 v68, 0xbfb8aa3b, v66
	v_exp_f32_e32 v68, v68
	v_rcp_f32_e32 v43, v67
	s_nop 0
	v_mul_f32_e32 v43, v44, v43
	v_mul_f32_e32 v44, v135, v142
	v_mul_f32_e32 v44, v44, v189
	v_add_f32_e32 v67, 1.0, v68
	v_mul_f32_e32 v43, v43, v44
	v_cvt_pk_bf16_f32 v43, v43, s0
	global_store_short v[94:95], v43, off
	v_lshlrev_b32_e32 v44, 16, v197
	v_mul_f32_e32 v68, 0xbfb8aa3b, v44
	v_exp_f32_e32 v68, v68
	v_rcp_f32_e32 v43, v67
	s_nop 0
	v_mul_f32_e32 v43, v66, v43
	v_mul_f32_e32 v66, v161, v144
	v_mul_f32_e32 v66, v66, v189
	v_add_f32_e32 v67, 1.0, v68
	v_mul_f32_e32 v43, v43, v66
	v_cvt_pk_bf16_f32 v43, v43, s0
	global_store_short v[92:93], v43, off
	v_lshlrev_b32_e32 v66, 16, v195
	v_mul_f32_e32 v68, 0xbfb8aa3b, v66
	v_exp_f32_e32 v68, v68
	v_rcp_f32_e32 v43, v67
	s_nop 0
	v_mul_f32_e32 v43, v44, v43
	v_mul_f32_e32 v44, v162, v145
	v_mul_f32_e32 v44, v44, v189
	v_add_f32_e32 v67, 1.0, v68
	v_mul_f32_e32 v43, v43, v44
	v_cvt_pk_bf16_f32 v43, v43, s0
	global_store_short v[90:91], v43, off
	v_lshlrev_b32_e32 v44, 16, v193
	v_mul_f32_e32 v68, 0xbfb8aa3b, v44
	v_exp_f32_e32 v68, v68
	v_rcp_f32_e32 v43, v67
	s_nop 0
	v_mul_f32_e32 v43, v66, v43
	v_mul_f32_e32 v66, v163, v146
	v_mul_f32_e32 v66, v66, v189
	v_add_f32_e32 v67, 1.0, v68
	v_mul_f32_e32 v43, v43, v66
	v_cvt_pk_bf16_f32 v43, v43, s0
	global_store_short v[88:89], v43, off
	v_lshlrev_b32_e32 v66, 16, v149
	v_mul_f32_e32 v68, 0xbfb8aa3b, v66
	v_exp_f32_e32 v68, v68
	v_rcp_f32_e32 v43, v67
	s_nop 0
	v_mul_f32_e32 v43, v44, v43
	v_mul_f32_e32 v44, v164, v148
	v_mul_f32_e32 v44, v44, v189
	v_add_f32_e32 v67, 1.0, v68
	v_mul_f32_e32 v43, v43, v44
	v_cvt_pk_bf16_f32 v43, v43, s0
	global_store_short v[86:87], v43, off
	v_lshlrev_b32_e32 v44, 16, v125
	v_mul_f32_e32 v68, 0xbfb8aa3b, v44
	v_exp_f32_e32 v68, v68
	v_rcp_f32_e32 v43, v67
	s_nop 0
	v_mul_f32_e32 v43, v66, v43
	v_mul_f32_e32 v66, v165, v150
	v_mul_f32_e32 v66, v66, v189
	v_add_f32_e32 v67, 1.0, v68
	v_mul_f32_e32 v43, v43, v66
	v_cvt_pk_bf16_f32 v43, v43, s0
	global_store_short v[84:85], v43, off
	v_lshlrev_b32_e32 v66, 16, v123
	v_mul_f32_e32 v68, 0xbfb8aa3b, v66
	v_exp_f32_e32 v68, v68
	v_rcp_f32_e32 v43, v67
	s_nop 0
	v_mul_f32_e32 v43, v44, v43
	v_mul_f32_e32 v44, v166, v153
	v_mul_f32_e32 v44, v44, v189
	v_add_f32_e32 v67, 1.0, v68
	v_mul_f32_e32 v43, v43, v44
	v_cvt_pk_bf16_f32 v43, v43, s0
	global_store_short v[82:83], v43, off
	v_lshlrev_b32_e32 v44, 16, v45
; __device__ __forceinline__ int crow(int r, int hi) { return (r & 3) + 8 * (r >> 2) + 4 * hi; }
; __device__ __forceinline__ float bf2f(bf16_t v) { return __uint_as_float((unsigned)v << 16); }
; __device__ __forceinline__ bf16_t f2bf(float f) { return (bf16_t)(cvtpk(f, 0.f) & 0xffffu); }
; template <int MODE>
; __device__ __forceinline__ void attn_unit(const Tensors& T0, int ureq, int b, int hh, int qblk, LAS3 char* shm, const bool dummy = false) {
;     ...
; #pragma unroll
;       for (int d = 0; d < ND; ++d) { const float gsub = T.subg[d * 32 + r32];
;         if (d + 1 < ND) {
; #pragma unroll
;           for (int r = 0; r < 16; ++r) gv[(d + 1) & 1][r] = gpb[(size_t)crow(r, hi) * 2048 + (d + 1) * 32]; }
; #pragma unroll
;         for (int r = 0; r < 16; ++r) { const float g = bf2f(gv[d & 1][r]); const float sg = g / (1.0f + __expf(-g));
;           gpb[(size_t)crow(r, hi) * 2048 + d * 32] = f2bf(o[d][r] * ss[r] * gsub * sg); } }
	v_mul_f32_e32 v45, 0xbfb8aa3b, v44
	v_exp_f32_e32 v45, v45
	v_rcp_f32_e32 v43, v67
	s_nop 0
	v_mul_f32_e32 v43, v66, v43
	v_mul_f32_e32 v66, v167, v156
	v_mul_f32_e32 v66, v66, v189
	v_add_f32_e32 v45, 1.0, v45
	v_mul_f32_e32 v43, v43, v66
	v_cvt_pk_bf16_f32 v43, v43, s0
	global_store_short v[80:81], v43, off
	v_lshlrev_b32_e32 v66, 16, v121
	v_mul_f32_e32 v67, 0xbfb8aa3b, v66
	v_exp_f32_e32 v67, v67
	v_rcp_f32_e32 v43, v45
	s_nop 0
	v_mul_f32_e32 v43, v44, v43
	v_mul_f32_e32 v44, v168, v155
	v_mul_f32_e32 v44, v44, v189
	v_add_f32_e32 v45, 1.0, v67
	v_mul_f32_e32 v43, v43, v44
	v_cvt_pk_bf16_f32 v43, v43, s0
	global_store_short v[78:79], v43, off
	v_lshlrev_b32_e32 v44, 16, v46
	v_mul_f32_e32 v46, 0xbfb8aa3b, v44
	v_exp_f32_e32 v46, v46
	v_rcp_f32_e32 v43, v45
	s_nop 0
	v_mul_f32_e32 v43, v66, v43
	v_mul_f32_e32 v45, v110, v117
	v_mul_f32_e32 v45, v45, v177
	v_add_f32_e32 v46, 1.0, v46
	v_mul_f32_e32 v43, v43, v45
	v_cvt_pk_bf16_f32 v43, v43, s0
	global_store_short v[18:19], v43, off offset:2240
	v_lshlrev_b32_e32 v19, 16, v47
	v_mul_f32_e32 v43, 0xbfb8aa3b, v19
	v_exp_f32_e32 v43, v43
	v_rcp_f32_e32 v18, v46
	s_nop 0
	v_mul_f32_e32 v18, v44, v18
	v_mul_f32_e32 v44, v111, v118
	v_mul_f32_e32 v44, v44, v177
	v_add_f32_e32 v43, 1.0, v43
	v_mul_f32_e32 v18, v18, v44
	v_cvt_pk_bf16_f32 v18, v18, s0
	global_store_short v[60:61], v18, off
	v_lshlrev_b32_e32 v44, 16, v62
	v_mul_f32_e32 v45, 0xbfb8aa3b, v44
	v_exp_f32_e32 v45, v45
	v_rcp_f32_e32 v18, v43
	s_nop 0
	v_mul_f32_e32 v18, v19, v18
	v_mul_f32_e32 v19, v112, v119
	v_mul_f32_e32 v19, v19, v177
	v_add_f32_e32 v43, 1.0, v45
	v_mul_f32_e32 v18, v18, v19
	v_cvt_pk_bf16_f32 v18, v18, s0
	global_store_short v[58:59], v18, off
	v_lshlrev_b32_e32 v19, 16, v63
	v_mul_f32_e32 v45, 0xbfb8aa3b, v19
	v_exp_f32_e32 v45, v45
	v_rcp_f32_e32 v18, v43
	s_nop 0
	v_mul_f32_e32 v18, v44, v18
	v_mul_f32_e32 v43, v113, v122
	v_mul_f32_e32 v43, v43, v177
	v_add_f32_e32 v44, 1.0, v45
	v_mul_f32_e32 v18, v18, v43
	v_cvt_pk_bf16_f32 v18, v18, s0
	global_store_short v[56:57], v18, off
	v_lshlrev_b32_e32 v43, 16, v64
	v_mul_f32_e32 v45, 0xbfb8aa3b, v43
	v_exp_f32_e32 v45, v45
	v_rcp_f32_e32 v18, v44
	s_nop 0
	v_mul_f32_e32 v18, v19, v18
	v_mul_f32_e32 v19, v114, v124
	v_mul_f32_e32 v19, v19, v177
	v_add_f32_e32 v44, 1.0, v45
	v_mul_f32_e32 v18, v18, v19
	v_cvt_pk_bf16_f32 v18, v18, s0
	global_store_short v[54:55], v18, off
	v_lshlrev_b32_e32 v19, 16, v65
	v_mul_f32_e32 v45, 0xbfb8aa3b, v19
	v_exp_f32_e32 v45, v45
	v_rcp_f32_e32 v18, v44
	s_nop 0
	v_mul_f32_e32 v18, v43, v18
	v_mul_f32_e32 v43, v115, v126
	v_mul_f32_e32 v43, v43, v177
	v_add_f32_e32 v44, 1.0, v45
	v_mul_f32_e32 v18, v18, v43
	v_cvt_pk_bf16_f32 v18, v18, s0
	global_store_short v[52:53], v18, off
	v_lshlrev_b32_e32 v42, 16, v42
	v_mul_f32_e32 v43, 0xbfb8aa3b, v42
	v_exp_f32_e32 v43, v43
	v_rcp_f32_e32 v18, v44
	s_nop 0
	v_mul_f32_e32 v18, v19, v18
	v_mul_f32_e32 v19, v116, v140
	v_mul_f32_e32 v19, v19, v177
	v_add_f32_e32 v43, 1.0, v43
	v_mul_f32_e32 v18, v18, v19
	v_cvt_pk_bf16_f32 v18, v18, s0
	global_store_short v[50:51], v18, off
	v_lshlrev_b32_e32 v19, 16, v41
	v_mul_f32_e32 v41, 0xbfb8aa3b, v19
	v_exp_f32_e32 v41, v41
	v_rcp_f32_e32 v18, v43
	s_nop 0
	v_mul_f32_e32 v18, v42, v18
	v_mul_f32_e32 v42, v120, v142
	v_mul_f32_e32 v42, v42, v177
	v_add_f32_e32 v41, 1.0, v41
	v_mul_f32_e32 v18, v18, v42
	v_cvt_pk_bf16_f32 v18, v18, s0
	global_store_short v[48:49], v18, off
	v_mul_f32_e32 v42, 0xbfb8aa3b, v40
	v_exp_f32_e32 v42, v42
	v_rcp_f32_e32 v18, v41
	s_nop 0
	v_mul_f32_e32 v18, v19, v18
	v_mul_f32_e32 v19, v134, v144
	v_mul_f32_e32 v19, v19, v177
	v_add_f32_e32 v41, 1.0, v42
	v_mul_f32_e32 v18, v18, v19
	v_cvt_pk_bf16_f32 v18, v18, s0
	global_store_short v[32:33], v18, off
	s_waitcnt vmcnt(30)
	v_lshlrev_b32_e32 v19, 16, v39
	v_mul_f32_e32 v32, 0xbfb8aa3b, v19
	v_exp_f32_e32 v32, v32
	v_rcp_f32_e32 v18, v41
	s_nop 0
	v_mul_f32_e32 v18, v40, v18
	v_mul_f32_e32 v33, v136, v145
	v_mul_f32_e32 v33, v33, v177
	v_add_f32_e32 v32, 1.0, v32
	v_mul_f32_e32 v18, v18, v33
	v_cvt_pk_bf16_f32 v18, v18, s0
	global_store_short v[30:31], v18, off
	s_waitcnt vmcnt(30)
	v_lshlrev_b32_e32 v30, 16, v38
	v_mul_f32_e32 v31, 0xbfb8aa3b, v30
	v_exp_f32_e32 v31, v31
	v_rcp_f32_e32 v18, v32
	s_nop 0
	v_mul_f32_e32 v18, v19, v18
	v_mul_f32_e32 v19, v137, v146
	v_mul_f32_e32 v19, v19, v177
	v_add_f32_e32 v31, 1.0, v31
	v_mul_f32_e32 v18, v18, v19
	v_cvt_pk_bf16_f32 v18, v18, s0
	global_store_short v[28:29], v18, off
	s_waitcnt vmcnt(30)
	v_lshlrev_b32_e32 v19, 16, v37
	v_mul_f32_e32 v28, 0xbfb8aa3b, v19
	v_exp_f32_e32 v28, v28
	v_rcp_f32_e32 v18, v31
	s_nop 0
	v_mul_f32_e32 v18, v30, v18
	v_mul_f32_e32 v29, v138, v148
	v_mul_f32_e32 v29, v29, v177
	v_add_f32_e32 v28, 1.0, v28
	v_mul_f32_e32 v18, v18, v29
	v_cvt_pk_bf16_f32 v18, v18, s0
	global_store_short v[26:27], v18, off
	s_waitcnt vmcnt(30)
	v_lshlrev_b32_e32 v26, 16, v36
	v_mul_f32_e32 v27, 0xbfb8aa3b, v26
	v_exp_f32_e32 v27, v27
	v_rcp_f32_e32 v18, v28
	s_nop 0
	v_mul_f32_e32 v18, v19, v18
	v_mul_f32_e32 v19, v139, v150
	v_mul_f32_e32 v19, v19, v177
	v_add_f32_e32 v27, 1.0, v27
	v_mul_f32_e32 v18, v18, v19
	v_cvt_pk_bf16_f32 v18, v18, s0
	global_store_short v[24:25], v18, off
	s_waitcnt vmcnt(30)
	v_lshlrev_b32_e32 v19, 16, v35
	v_mul_f32_e32 v24, 0xbfb8aa3b, v19
	v_exp_f32_e32 v24, v24
	v_rcp_f32_e32 v18, v27
	s_nop 0
	v_mul_f32_e32 v18, v26, v18
	v_mul_f32_e32 v25, v141, v153
	v_mul_f32_e32 v25, v25, v177
	v_add_f32_e32 v24, 1.0, v24
	v_mul_f32_e32 v18, v18, v25
	v_cvt_pk_bf16_f32 v18, v18, s0
	global_store_short v[22:23], v18, off
	s_waitcnt vmcnt(30)
	v_lshlrev_b32_e32 v22, 16, v34
	v_mul_f32_e32 v23, 0xbfb8aa3b, v22
	v_exp_f32_e32 v23, v23
	v_rcp_f32_e32 v18, v24
	s_nop 0
	v_mul_f32_e32 v18, v19, v18
	v_mul_f32_e32 v19, v143, v156
	v_mul_f32_e32 v19, v19, v177
	v_add_f32_e32 v23, 1.0, v23
	v_mul_f32_e32 v18, v18, v19
	v_cvt_pk_bf16_f32 v18, v18, s0
	global_store_short v[20:21], v18, off
	v_mul_f32_e32 v19, v147, v155
	v_rcp_f32_e32 v18, v23
	s_nop 0
	v_mul_f32_e32 v18, v22, v18
	v_mul_f32_e32 v19, v19, v177
	v_mul_f32_e32 v18, v18, v19
	v_cvt_pk_bf16_f32 v18, v18, s0
	global_store_short v[16:17], v18, off
	s_branch .LBB0_82

; __device__ __forceinline__ int crow(int r, int hi) { return (r & 3) + 8 * (r >> 2) + 4 * hi; }
; __device__ __forceinline__ float bf2f(bf16_t v) { return __uint_as_float((unsigned)v << 16); }
; __device__ __forceinline__ bf16_t f2bf(float f) { return (bf16_t)(cvtpk(f, 0.f) & 0xffffu); }
; template <int MODE>
; __device__ __forceinline__ void attn_unit(const Tensors& T0, int ureq, int b, int hh, int qblk, LAS3 char* shm, const bool dummy = false) {
;     ...
;   if (hi == 0) wsf[32 + r32] = l_reg;
;   asm volatile("s_waitcnt lgkmcnt(0)" ::: "memory");
;   float rli[16];
; #pragma unroll
;   for (int r = 0; r < 16; ++r) rli[r] = 1.0f / wsf[32 + crow(r, hi)];
;     ...
;     bf16_t* const gpb = T.G + (size_t)(rowbase + q0w) * 2048 + (hh * 4 + sub) * 64 + r32; bf16_t gv[2][16];
; #pragma unroll
;     for (int d = 0; d < ND; ++d)
; #pragma unroll
;       for (int r = 0; r < 16; ++r) gv[d][r] = gpb[(size_t)crow(r, hi) * 2048 + d * 32];
; #pragma unroll
;     for (int d = 0; d < ND; ++d)
; #pragma unroll
;       for (int r = 0; r < 16; ++r) { const float g = bf2f(gv[d][r]); const float sg = g / (1.0f + __expf(-g));
;         gpb[(size_t)crow(r, hi) * 2048 + d * 32] = f2bf(o[d][r] * rli[r] * sg); }
.LBB0_147:
	s_or_b64 exec, exec, s[38:39]
	s_waitcnt lgkmcnt(0)
	v_lshl_add_u32 v0, v124, 2, s69
	ds_read_b128 v[2:5], v0 offset:128
	ds_read_b128 v[6:9], v0 offset:160
	v_mov_b32_e32 v49, v1
	v_mov_b32_e32 v107, v1
	v_mov_b32_e32 v109, v1
	s_waitcnt lgkmcnt(1)
	v_rcp_f32_e32 v105, v2
	s_nop 0
	v_mov_b32_e32 v15, v1
	v_rcp_f32_e32 v104, v3
	s_nop 0
	v_mov_b32_e32 v111, v1
	v_rcp_f32_e32 v101, v4
	s_nop 0
	v_mov_b32_e32 v113, v1
	s_waitcnt lgkmcnt(0)
	v_rcp_f32_e32 v99, v5
	s_nop 0
	v_mov_b32_e32 v115, v1
	v_rcp_f32_e32 v97, v6
	s_nop 0
	v_mov_b32_e32 v117, v1
	v_rcp_f32_e32 v95, v7
	s_nop 0
	v_rcp_f32_e32 v94, v8
	s_nop 0
	ds_read_b128 v[2:5], v0 offset:192
	ds_read_b128 v[10:13], v0 offset:224
	s_waitcnt lgkmcnt(1)
	v_rcp_f32_e32 v102, v9
	s_nop 0
	v_mov_b32_e32 v125, v1
	v_rcp_f32_e32 v98, v2
	s_nop 0
	v_mul_f32_e32 v32, v32, v105
	v_rcp_f32_e32 v96, v3
	s_nop 0
	v_mov_b32_e32 v9, v1
	v_rcp_f32_e32 v93, v4
	s_nop 0
	v_mul_f32_e32 v33, v33, v104
	s_waitcnt lgkmcnt(0)
	v_rcp_f32_e32 v92, v5
	s_nop 0
	v_mul_f32_e32 v34, v34, v101
	v_rcp_f32_e32 v91, v10
	s_nop 0
	v_mul_f32_e32 v16, v16, v105
	v_rcp_f32_e32 v90, v11
	s_nop 0
	s_lshl_b64 s[4:5], s[54:55], 12
	s_add_u32 s4, s10, s4
	s_addc_u32 s5, s11, s5
	s_add_u32 s4, s4, s66
	s_addc_u32 s5, s5, s67
	v_lshlrev_b32_e32 v0, 1, v123
	v_lshl_add_u64 v[2:3], s[4:5], 0, v[0:1]
	v_lshlrev_b32_e32 v0, 14, v122
	v_lshl_add_u64 v[54:55], v[2:3], 0, v[0:1]
	flat_load_ushort v126, v[54:55]
	v_rcp_f32_e32 v103, v12
	s_nop 0
	v_or_b32_e32 v10, 0x8000, v0
	v_rcp_f32_e32 v100, v13
	s_nop 0
	v_or_b32_e32 v4, 0x1000, v0
	v_mov_b32_e32 v5, v1
	v_lshl_add_u64 v[118:119], v[2:3], 0, v[4:5]
	flat_load_ushort v127, v[118:119]
	v_or_b32_e32 v6, 0x2000, v0
	v_mov_b32_e32 v7, v1
	v_lshl_add_u64 v[120:121], v[2:3], 0, v[6:7]
	flat_load_ushort v128, v[120:121]
	v_or_b32_e32 v8, 0x3000, v0
	v_lshl_add_u64 v[122:123], v[2:3], 0, v[8:9]
	v_mov_b32_e32 v11, v1
	v_or_b32_e32 v12, 0x9000, v0
	v_mov_b32_e32 v13, v1
	v_or_b32_e32 v14, 0xa000, v0
	v_lshl_add_u64 v[88:89], v[2:3], 0, v[10:11]
	v_lshl_add_u64 v[86:87], v[2:3], 0, v[12:13]
	v_lshl_add_u64 v[84:85], v[2:3], 0, v[14:15]
	flat_load_ushort v129, v[122:123]
	flat_load_ushort v130, v[88:89]
	flat_load_ushort v131, v[86:87]
	flat_load_ushort v132, v[84:85]
	flat_load_ushort v133, v[54:55] offset:64
	v_or_b32_e32 v48, 0xb000, v0
	v_or_b32_e32 v106, 0x10000, v0
	v_or_b32_e32 v108, 0x11000, v0
	v_or_b32_e32 v110, 0x12000, v0
	v_or_b32_e32 v112, 0x13000, v0
	v_or_b32_e32 v114, 0x18000, v0
	v_or_b32_e32 v116, 0x19000, v0
	v_or_b32_e32 v124, 0x1a000, v0
	v_or_b32_e32 v0, 0x1b000, v0
	v_lshl_add_u64 v[82:83], v[2:3], 0, v[48:49]
	v_lshl_add_u64 v[80:81], v[2:3], 0, v[106:107]
	v_lshl_add_u64 v[78:79], v[2:3], 0, v[108:109]
	v_lshl_add_u64 v[76:77], v[2:3], 0, v[110:111]
	v_lshl_add_u64 v[74:75], v[2:3], 0, v[112:113]
	v_lshl_add_u64 v[72:73], v[2:3], 0, v[114:115]
	v_lshl_add_u64 v[70:71], v[2:3], 0, v[116:117]
	v_lshl_add_u64 v[68:69], v[2:3], 0, v[124:125]
	v_lshl_add_u64 v[66:67], v[2:3], 0, v[0:1]
	v_lshl_add_u64 v[2:3], v[2:3], 0, 64
	v_lshl_add_u64 v[50:51], v[2:3], 0, v[48:49]
	v_lshl_add_u64 v[48:49], v[2:3], 0, v[106:107]
	v_lshl_add_u64 v[64:65], v[2:3], 0, v[4:5]
	v_lshl_add_u64 v[52:53], v[2:3], 0, v[14:15]
	v_lshl_add_u64 v[14:15], v[2:3], 0, v[108:109]
	v_lshl_add_u64 v[62:63], v[2:3], 0, v[6:7]
	v_lshl_add_u64 v[60:61], v[2:3], 0, v[8:9]
	v_lshl_add_u64 v[58:59], v[2:3], 0, v[10:11]
	v_lshl_add_u64 v[56:57], v[2:3], 0, v[12:13]
	v_lshl_add_u64 v[12:13], v[2:3], 0, v[110:111]
	v_lshl_add_u64 v[10:11], v[2:3], 0, v[112:113]
	v_lshl_add_u64 v[8:9], v[2:3], 0, v[114:115]
	v_lshl_add_u64 v[6:7], v[2:3], 0, v[116:117]
	v_mul_f32_e32 v17, v17, v104
	s_add_i32 s33, s33, s3
	s_cmpk_gt_i32 s33, 0xfff
	s_waitcnt vmcnt(0) lgkmcnt(0)
	v_lshlrev_b32_e32 v106, 16, v126
	v_mul_f32_e32 v4, 0xbfb8aa3b, v106
	v_exp_f32_e32 v4, v4
	v_lshlrev_b32_e32 v127, 16, v127
	v_add_f32_e32 v107, 1.0, v4
	v_lshl_add_u64 v[4:5], v[2:3], 0, v[124:125]
	v_lshl_add_u64 v[2:3], v[2:3], 0, v[0:1]
	flat_load_ushort v124, v[82:83]
	flat_load_ushort v125, v[80:81]
	flat_load_ushort v126, v[78:79]
	flat_load_ushort v134, v[76:77]
	flat_load_ushort v135, v[74:75]
	flat_load_ushort v136, v[72:73]
	flat_load_ushort v137, v[70:71]
	flat_load_ushort v138, v[68:69]
	v_rcp_f32_e32 v0, v107
	s_nop 0
	v_mul_f32_e32 v0, v106, v0
	v_mul_f32_e32 v0, v32, v0
	v_cvt_pk_bf16_f32 v117, v0, s0
	v_mul_f32_e32 v0, 0xbfb8aa3b, v127
	v_exp_f32_e32 v0, v0
	flat_load_ushort v139, v[66:67]
	flat_load_ushort v140, v[64:65]
	flat_load_ushort v141, v[62:63]
	flat_load_ushort v116, v[60:61]
	flat_load_ushort v115, v[58:59]
	flat_load_ushort v114, v[56:57]
	flat_load_ushort v113, v[52:53]
	flat_load_ushort v112, v[50:51]
	v_lshlrev_b32_e32 v128, 16, v128
	v_add_f32_e32 v142, 1.0, v0
	flat_load_ushort v111, v[48:49]
	flat_load_ushort v110, v[14:15]
	flat_load_ushort v109, v[12:13]
	flat_load_ushort v108, v[10:11]
	flat_load_ushort v107, v[8:9]
	flat_load_ushort v106, v[6:7]
	flat_load_ushort v32, v[4:5]
	flat_load_ushort v0, v[2:3]
	s_waitcnt vmcnt(0) lgkmcnt(0)
; __device__ __forceinline__ int crow(int r, int hi) { return (r & 3) + 8 * (r >> 2) + 4 * hi; }
; __device__ __forceinline__ float bf2f(bf16_t v) { return __uint_as_float((unsigned)v << 16); }
; __device__ __forceinline__ bf16_t f2bf(float f) { return (bf16_t)(cvtpk(f, 0.f) & 0xffffu); }
; template <int MODE>
; __device__ __forceinline__ void attn_unit(const Tensors& T0, int ureq, int b, int hh, int qblk, LAS3 char* shm, const bool dummy = false) {
;     ...
;     for (int d = 0; d < ND; ++d)
; #pragma unroll
;       for (int r = 0; r < 16; ++r) { const float g = bf2f(gv[d][r]); const float sg = g / (1.0f + __expf(-g));
;         gpb[(size_t)crow(r, hi) * 2048 + d * 32] = f2bf(o[d][r] * rli[r] * sg); }
	v_lshlrev_b32_e32 v0, 16, v0
	flat_store_short v[54:55], v117
	v_mul_f32_e32 v143, 0xbfb8aa3b, v128
	v_exp_f32_e32 v143, v143
	v_rcp_f32_e32 v117, v142
	s_nop 0
	v_mul_f32_e32 v117, v127, v117
	v_mul_f32_e32 v33, v33, v117
	v_add_f32_e32 v127, 1.0, v143
	v_cvt_pk_bf16_f32 v33, v33, s0
	flat_store_short v[118:119], v33
	v_lshlrev_b32_e32 v118, 16, v129
	v_mul_f32_e32 v119, 0xbfb8aa3b, v118
	v_exp_f32_e32 v119, v119
	v_rcp_f32_e32 v33, v127
	s_nop 0
	v_mul_f32_e32 v33, v128, v33
	v_add_f32_e32 v117, 1.0, v119
	v_mul_f32_e32 v33, v34, v33
	v_cvt_pk_bf16_f32 v33, v33, s0
	flat_store_short v[120:121], v33
	v_lshlrev_b32_e32 v119, 16, v130
	v_mul_f32_e32 v120, 0xbfb8aa3b, v119
	v_exp_f32_e32 v120, v120
	v_mul_f32_e32 v34, v35, v99
	v_rcp_f32_e32 v33, v117
	s_nop 0
	v_mul_f32_e32 v33, v118, v33
	v_add_f32_e32 v35, 1.0, v120
	v_mul_f32_e32 v33, v34, v33
	v_cvt_pk_bf16_f32 v33, v33, s0
	flat_store_short v[122:123], v33
	v_lshlrev_b32_e32 v117, 16, v131
	v_mul_f32_e32 v120, 0xbfb8aa3b, v117
	v_exp_f32_e32 v120, v120
	v_rcp_f32_e32 v33, v35
	s_nop 0
	v_mul_f32_e32 v33, v119, v33
	v_mul_f32_e32 v34, v36, v97
	v_add_f32_e32 v35, 1.0, v120
	v_mul_f32_e32 v33, v34, v33
	v_cvt_pk_bf16_f32 v33, v33, s0
	flat_store_short v[88:89], v33
	v_lshlrev_b32_e32 v36, 16, v132
	v_mul_f32_e32 v88, 0xbfb8aa3b, v36
	v_exp_f32_e32 v88, v88
	v_rcp_f32_e32 v33, v35
	s_nop 0
	v_mul_f32_e32 v33, v117, v33
	v_mul_f32_e32 v34, v37, v95
	v_add_f32_e32 v35, 1.0, v88
	v_mul_f32_e32 v33, v34, v33
	v_cvt_pk_bf16_f32 v33, v33, s0
	flat_store_short v[86:87], v33
	v_lshlrev_b32_e32 v37, 16, v124
	v_mul_f32_e32 v86, 0xbfb8aa3b, v37
	v_exp_f32_e32 v86, v86
	v_rcp_f32_e32 v33, v35
	s_nop 0
	v_mul_f32_e32 v33, v36, v33
	v_mul_f32_e32 v34, v38, v94
	v_add_f32_e32 v35, 1.0, v86
	v_mul_f32_e32 v33, v34, v33
	v_cvt_pk_bf16_f32 v33, v33, s0
	flat_store_short v[84:85], v33
	v_lshlrev_b32_e32 v36, 16, v125
	v_mul_f32_e32 v84, 0xbfb8aa3b, v36
	v_exp_f32_e32 v84, v84
	v_rcp_f32_e32 v33, v35
	s_nop 0
	v_mul_f32_e32 v33, v37, v33
	v_mul_f32_e32 v34, v39, v102
	v_add_f32_e32 v35, 1.0, v84
	v_mul_f32_e32 v33, v34, v33
	v_cvt_pk_bf16_f32 v33, v33, s0
	flat_store_short v[82:83], v33
	v_lshlrev_b32_e32 v37, 16, v126
	v_mul_f32_e32 v39, 0xbfb8aa3b, v37
	v_exp_f32_e32 v39, v39
	v_rcp_f32_e32 v33, v35
	s_nop 0
	v_mul_f32_e32 v33, v36, v33
	v_mul_f32_e32 v34, v40, v98
	v_add_f32_e32 v35, 1.0, v39
	v_mul_f32_e32 v33, v34, v33
	v_cvt_pk_bf16_f32 v33, v33, s0
	flat_store_short v[80:81], v33
	v_lshlrev_b32_e32 v36, 16, v134
	v_mul_f32_e32 v39, 0xbfb8aa3b, v36
	v_exp_f32_e32 v39, v39
	v_rcp_f32_e32 v33, v35
	s_nop 0
	v_mul_f32_e32 v33, v37, v33
	v_mul_f32_e32 v34, v41, v96
	v_add_f32_e32 v35, 1.0, v39
	v_mul_f32_e32 v33, v34, v33
	v_cvt_pk_bf16_f32 v33, v33, s0
	flat_store_short v[78:79], v33
	v_lshlrev_b32_e32 v37, 16, v135
	v_mul_f32_e32 v39, 0xbfb8aa3b, v37
	v_exp_f32_e32 v39, v39
	v_rcp_f32_e32 v33, v35
	s_nop 0
	v_mul_f32_e32 v33, v36, v33
	v_mul_f32_e32 v34, v42, v93
	v_add_f32_e32 v35, 1.0, v39
	v_mul_f32_e32 v33, v34, v33
	v_cvt_pk_bf16_f32 v33, v33, s0
	flat_store_short v[76:77], v33
	v_lshlrev_b32_e32 v36, 16, v136
	v_mul_f32_e32 v39, 0xbfb8aa3b, v36
	v_exp_f32_e32 v39, v39
	v_rcp_f32_e32 v33, v35
	s_nop 0
	v_mul_f32_e32 v33, v37, v33
	v_mul_f32_e32 v34, v43, v92
	v_add_f32_e32 v35, 1.0, v39
	v_mul_f32_e32 v33, v34, v33
	v_cvt_pk_bf16_f32 v33, v33, s0
	flat_store_short v[74:75], v33
	v_lshlrev_b32_e32 v37, 16, v137
	v_mul_f32_e32 v39, 0xbfb8aa3b, v37
	v_exp_f32_e32 v39, v39
	v_rcp_f32_e32 v33, v35
	s_nop 0
	v_mul_f32_e32 v33, v36, v33
	v_mul_f32_e32 v34, v44, v91
	v_add_f32_e32 v35, 1.0, v39
	v_mul_f32_e32 v33, v34, v33
	v_cvt_pk_bf16_f32 v33, v33, s0
	flat_store_short v[72:73], v33
	v_lshlrev_b32_e32 v36, 16, v138
	v_mul_f32_e32 v39, 0xbfb8aa3b, v36
	v_exp_f32_e32 v39, v39
	v_rcp_f32_e32 v33, v35
	s_nop 0
	v_mul_f32_e32 v33, v37, v33
	v_mul_f32_e32 v34, v45, v90
	v_add_f32_e32 v35, 1.0, v39
	v_mul_f32_e32 v33, v34, v33
	v_cvt_pk_bf16_f32 v33, v33, s0
	flat_store_short v[70:71], v33
	v_lshlrev_b32_e32 v37, 16, v139
	v_mul_f32_e32 v39, 0xbfb8aa3b, v37
	v_exp_f32_e32 v39, v39
	v_rcp_f32_e32 v33, v35
	s_nop 0
	v_mul_f32_e32 v33, v36, v33
	v_mul_f32_e32 v34, v46, v103
	v_add_f32_e32 v35, 1.0, v39
	v_mul_f32_e32 v33, v34, v33
	v_cvt_pk_bf16_f32 v33, v33, s0
	flat_store_short v[68:69], v33
	v_lshlrev_b32_e32 v36, 16, v133
	v_mul_f32_e32 v39, 0xbfb8aa3b, v36
	v_exp_f32_e32 v39, v39
	v_rcp_f32_e32 v33, v35
	s_nop 0
	v_mul_f32_e32 v33, v37, v33
	v_mul_f32_e32 v34, v47, v100
	v_add_f32_e32 v35, 1.0, v39
	v_mul_f32_e32 v33, v34, v33
	v_cvt_pk_bf16_f32 v33, v33, s0
	flat_store_short v[66:67], v33
	v_lshlrev_b32_e32 v37, 16, v140
	v_mul_f32_e32 v39, 0xbfb8aa3b, v37
; __device__ __forceinline__ int crow(int r, int hi) { return (r & 3) + 8 * (r >> 2) + 4 * hi; }
; __device__ __forceinline__ float bf2f(bf16_t v) { return __uint_as_float((unsigned)v << 16); }
; __device__ __forceinline__ bf16_t f2bf(float f) { return (bf16_t)(cvtpk(f, 0.f) & 0xffffu); }
; #define ATT_WAIT_BAR(N) asm volatile("s_waitcnt vmcnt(" #N ") lgkmcnt(0)\n\ts_barrier" ::: "memory")
; template <int MODE>
; __device__ __forceinline__ void attn_unit(const Tensors& T0, int ureq, int b, int hh, int qblk, LAS3 char* shm, const bool dummy = false) {
;     ...
;     for (int d = 0; d < ND; ++d)
; #pragma unroll
;       for (int r = 0; r < 16; ++r) { const float g = bf2f(gv[d][r]); const float sg = g / (1.0f + __expf(-g));
;         gpb[(size_t)crow(r, hi) * 2048 + d * 32] = f2bf(o[d][r] * rli[r] * sg); }
;   }
;   if (!MODE && dummy) {
; #pragma unroll
;     for (int d = 0; d < ND; ++d) asm volatile("" :: "v"(o[d]));
;     asm volatile("" :: "v"(rli[0]), "v"(rli[15]));
;   }
;   ATT_WAIT_BAR(0);
	v_exp_f32_e32 v39, v39
	v_rcp_f32_e32 v33, v35
	s_nop 0
	v_mul_f32_e32 v33, v36, v33
	v_mul_f32_e32 v16, v16, v33
	v_add_f32_e32 v34, 1.0, v39
	v_cvt_pk_bf16_f32 v16, v16, s0
	flat_store_short v[54:55], v16 offset:64
	v_lshlrev_b32_e32 v35, 16, v141
	v_mul_f32_e32 v38, 0xbfb8aa3b, v35
	v_exp_f32_e32 v38, v38
	v_rcp_f32_e32 v16, v34
	s_nop 0
	v_mul_f32_e32 v16, v37, v16
	v_mul_f32_e32 v16, v17, v16
	v_add_f32_e32 v33, 1.0, v38
	v_cvt_pk_bf16_f32 v16, v16, s0
	flat_store_short v[64:65], v16
	v_lshlrev_b32_e32 v34, 16, v116
	v_mul_f32_e32 v37, 0xbfb8aa3b, v34
	v_exp_f32_e32 v37, v37
	v_mul_f32_e32 v17, v18, v101
	v_rcp_f32_e32 v16, v33
	s_nop 0
	v_mul_f32_e32 v16, v35, v16
	v_add_f32_e32 v18, 1.0, v37
	v_mul_f32_e32 v16, v17, v16
	v_cvt_pk_bf16_f32 v16, v16, s0
	flat_store_short v[62:63], v16
	v_lshlrev_b32_e32 v33, 16, v115
	v_mul_f32_e32 v36, 0xbfb8aa3b, v33
	v_exp_f32_e32 v36, v36
	v_rcp_f32_e32 v16, v18
	s_nop 0
	v_mul_f32_e32 v16, v34, v16
	v_mul_f32_e32 v17, v19, v99
	v_add_f32_e32 v18, 1.0, v36
	v_mul_f32_e32 v16, v17, v16
	v_cvt_pk_bf16_f32 v16, v16, s0
	flat_store_short v[60:61], v16
	v_lshlrev_b32_e32 v19, 16, v114
	v_mul_f32_e32 v35, 0xbfb8aa3b, v19
	v_exp_f32_e32 v35, v35
	v_rcp_f32_e32 v16, v18
	s_nop 0
	v_mul_f32_e32 v16, v33, v16
	v_mul_f32_e32 v17, v20, v97
	v_add_f32_e32 v18, 1.0, v35
	v_mul_f32_e32 v16, v17, v16
	v_cvt_pk_bf16_f32 v16, v16, s0
	flat_store_short v[58:59], v16
	v_lshlrev_b32_e32 v20, 16, v113
	v_mul_f32_e32 v34, 0xbfb8aa3b, v20
	v_exp_f32_e32 v34, v34
	v_rcp_f32_e32 v16, v18
	s_nop 0
	v_mul_f32_e32 v16, v19, v16
	v_mul_f32_e32 v17, v21, v95
	v_add_f32_e32 v18, 1.0, v34
	v_mul_f32_e32 v16, v17, v16
	v_cvt_pk_bf16_f32 v16, v16, s0
	flat_store_short v[56:57], v16
	v_lshlrev_b32_e32 v19, 16, v112
	v_mul_f32_e32 v33, 0xbfb8aa3b, v19
	v_exp_f32_e32 v33, v33
	v_rcp_f32_e32 v16, v18
	s_nop 0
	v_mul_f32_e32 v16, v20, v16
	v_mul_f32_e32 v17, v22, v94
	v_add_f32_e32 v18, 1.0, v33
	v_mul_f32_e32 v16, v17, v16
	v_cvt_pk_bf16_f32 v16, v16, s0
	flat_store_short v[52:53], v16
	v_lshlrev_b32_e32 v20, 16, v111
	v_mul_f32_e32 v22, 0xbfb8aa3b, v20
	v_exp_f32_e32 v22, v22
	v_rcp_f32_e32 v16, v18
	s_nop 0
	v_mul_f32_e32 v16, v19, v16
	v_mul_f32_e32 v17, v23, v102
	v_add_f32_e32 v18, 1.0, v22
	v_mul_f32_e32 v16, v17, v16
	v_cvt_pk_bf16_f32 v16, v16, s0
	flat_store_short v[50:51], v16
	v_lshlrev_b32_e32 v19, 16, v110
	v_mul_f32_e32 v22, 0xbfb8aa3b, v19
	v_exp_f32_e32 v22, v22
	v_rcp_f32_e32 v16, v18
	s_nop 0
	v_mul_f32_e32 v16, v20, v16
	v_mul_f32_e32 v17, v24, v98
	v_add_f32_e32 v18, 1.0, v22
	v_mul_f32_e32 v16, v17, v16
	v_cvt_pk_bf16_f32 v16, v16, s0
	flat_store_short v[48:49], v16
	v_lshlrev_b32_e32 v20, 16, v109
	v_mul_f32_e32 v22, 0xbfb8aa3b, v20
	v_exp_f32_e32 v22, v22
	v_rcp_f32_e32 v16, v18
	s_nop 0
	v_mul_f32_e32 v16, v19, v16
	v_mul_f32_e32 v17, v25, v96
	v_add_f32_e32 v18, 1.0, v22
	v_mul_f32_e32 v16, v17, v16
	v_cvt_pk_bf16_f32 v16, v16, s0
	flat_store_short v[14:15], v16
	v_lshlrev_b32_e32 v16, 16, v108
	v_mul_f32_e32 v17, 0xbfb8aa3b, v16
	v_exp_f32_e32 v17, v17
	v_rcp_f32_e32 v14, v18
	s_nop 0
	v_mul_f32_e32 v14, v20, v14
	v_add_f32_e32 v17, 1.0, v17
	v_mul_f32_e32 v15, v26, v93
	v_mul_f32_e32 v14, v15, v14
	v_cvt_pk_bf16_f32 v14, v14, s0
	flat_store_short v[12:13], v14
	v_lshlrev_b32_e32 v14, 16, v107
	v_mul_f32_e32 v15, 0xbfb8aa3b, v14
	v_exp_f32_e32 v15, v15
	v_rcp_f32_e32 v12, v17
	s_nop 0
	v_mul_f32_e32 v12, v16, v12
	v_add_f32_e32 v15, 1.0, v15
	v_mul_f32_e32 v13, v27, v92
	v_mul_f32_e32 v12, v13, v12
	v_cvt_pk_bf16_f32 v12, v12, s0
	flat_store_short v[10:11], v12
	v_lshlrev_b32_e32 v12, 16, v106
	v_mul_f32_e32 v13, 0xbfb8aa3b, v12
	v_exp_f32_e32 v13, v13
	v_rcp_f32_e32 v10, v15
	s_nop 0
	v_mul_f32_e32 v10, v14, v10
	v_add_f32_e32 v13, 1.0, v13
	v_mul_f32_e32 v11, v28, v91
	v_mul_f32_e32 v10, v11, v10
	v_cvt_pk_bf16_f32 v10, v10, s0
	flat_store_short v[8:9], v10
	v_lshlrev_b32_e32 v10, 16, v32
	v_mul_f32_e32 v11, 0xbfb8aa3b, v10
	v_exp_f32_e32 v11, v11
	v_rcp_f32_e32 v8, v13
	s_nop 0
	v_mul_f32_e32 v8, v12, v8
	v_add_f32_e32 v11, 1.0, v11
	v_mul_f32_e32 v9, v29, v90
	v_mul_f32_e32 v8, v9, v8
	v_cvt_pk_bf16_f32 v8, v8, s0
	flat_store_short v[6:7], v8
	v_mul_f32_e32 v8, 0xbfb8aa3b, v0
	v_exp_f32_e32 v8, v8
	v_rcp_f32_e32 v6, v11
	s_nop 0
	v_mul_f32_e32 v6, v10, v6
	v_add_f32_e32 v8, 1.0, v8
	v_mul_f32_e32 v7, v30, v103
	v_mul_f32_e32 v6, v7, v6
	v_cvt_pk_bf16_f32 v6, v6, s0
	flat_store_short v[4:5], v6
	v_rcp_f32_e32 v4, v8
	s_nop 0
	v_mul_f32_e32 v0, v0, v4
	v_mul_f32_e32 v4, v31, v100
	v_mul_f32_e32 v0, v4, v0
	v_cvt_pk_bf16_f32 v0, v0, s0
	flat_store_short v[2:3], v0
	s_waitcnt vmcnt(0) lgkmcnt(0)
	s_barrier
	s_cbranch_scc1 .LBB0_222

; #define ATT_BAR_V(full) do { if (full) { if (MODE) ATT_WAIT_BAR(4); else ATT_WAIT_BAR(2); } else ATT_WAIT_BAR(0); } while (0)
; #define ATT_BAR_L() asm volatile("s_waitcnt lgkmcnt(0)\n\ts_barrier" ::: "memory")
; template <int MODE>
; __device__ __forceinline__ void attn_unit(const Tensors& T0, int ureq, int b, int hh, int qblk, LAS3 char* shm, const bool dummy = false) {
;     ...
;   if (MODE) { cbL = T.gtab[(16 + hh) * TABW]; cbR = T.gtab[(16 + hh) * TABW + TABW - 1]; lam = T.lamp[0]; } else { sinkv = T.sink[hh * 4 + sub] * LOG2E; }
;   bf16x8 qr[4];
; #pragma unroll
;   for (int d0 = 0; d0 < 4; ++d0) qr[d0] = *reinterpret_cast<const bf16x8*>(&Qw[(long)r32 * PQ + d0 * 16 + hi * 8]);
;   asm volatile("s_waitcnt vmcnt(0)" ::: "memory");
;   const int drow = 8 * wid + (lane >> 3);
;   const bf16_t* ksrc = Kh + (long)drow * PK + (((lane & 7) ^ ((drow >> 1) & 7)) * 8);
;   const bf16_t* vsrc = Vh + (long)drow * PK + ((((lane >> 2) & 1) ^ ((lane >> 4) & 1)) * 32) + (lane & 3) * 8;
;   const unsigned dwv = lds0 + wid * 1024;
;     ...
;   if (!(ATT_ABL == 2 && dummy)) { ATT_DMA(t_lo, 0); ATT_DMA(t_lo + 1, SLOTB); }
;   ATT_BAR_V(true);
;   if (grp == 1) { if (NT > 2 && !(ATT_ABL == 2 && dummy)) ATT_DMA(t_lo + 2, 2 * SLOTB); ATT_BAR_L(); }
.LBB0_156:
	s_or_b64 exec, exec, s[46:47]
	s_and_b32 s82, s19, s37
	s_and_b32 s19, s39, 3
	s_ashr_i32 s39, s38, 31
	s_ashr_i32 s37, s81, 6
	s_lshl_b64 s[46:47], s[38:39], 13
	s_add_u32 s46, s46, 0x8000
	s_addc_u32 s47, s47, 0
	s_lshl_b64 s[38:39], s[38:39], 12
	s_and_b64 s[4:5], s[4:5], exec
	s_cselect_b32 s5, s39, s47
	s_cselect_b32 s4, s38, s46
	s_lshl_b32 s38, s37, 5
	s_lshl_b32 s46, s82, 6
	s_and_b32 s38, s38, 32
	s_ashr_i32 s84, s81, 7
	s_or_b32 s85, s38, s46
	s_add_u32 s54, s4, s85
	s_addc_u32 s55, s5, 0
	s_lshl_b64 s[38:39], s[54:55], 11
	s_add_u32 s47, s44, s38
	s_addc_u32 s39, s45, s39
	s_lshl_b32 s38, s19, 2
	s_add_i32 s38, s84, s38
	s_lshl_b32 s44, s38, 6
	s_ashr_i32 s45, s44, 31
	s_lshl_b64 s[66:67], s[44:45], 1
	s_add_u32 s44, s47, s66
	s_addc_u32 s45, s39, s67
	s_lshl_b64 s[4:5], s[4:5], 10
	s_add_u32 s4, s42, s4
	s_addc_u32 s5, s43, s5
	s_lshl_b32 s19, s19, 7
	s_add_u32 s4, s4, s19
	s_addc_u32 s5, s5, 0
	s_ashr_i32 s39, s38, 31
	v_and_b32_e32 v123, 31, v16
	s_lshl_b64 s[38:39], s[38:39], 2
	v_bfe_u32 v122, v16, 5, 1
	s_add_u32 s38, s40, s38
	v_lshlrev_b32_e32 v0, 11, v123
	s_addc_u32 s39, s41, s39
	v_lshl_or_b32 v0, v122, 4, v0
	v_mov_b64_e32 v[2:3], s[38:39]
	v_lshl_add_u64 v[14:15], s[44:45], 0, v[0:1]
	global_load_dword v17, v[2:3], off
	s_nop 0
	global_load_dwordx4 v[2:5], v[14:15], off
	global_load_dwordx4 v[6:9], v[14:15], off offset:32
	global_load_dwordx4 v[10:13], v[14:15], off offset:64
	global_load_dwordx4 v[96:99], v[14:15], off offset:96
	v_bfe_u32 v18, v16, 3, 3
	v_lshl_or_b32 v14, s37, 3, v18
	v_ashrrev_i32_e32 v15, 31, v14
	v_lshlrev_b64 v[20:21], 10, v[14:15]
	v_lshrrev_b32_e32 v0, 1, v14
	v_lshl_add_u64 v[22:23], s[4:5], 0, v[20:21]
	v_xor_b32_e32 v0, v0, v16
	s_add_i32 s4, s46, 0xffffff80
	s_addk_i32 s46, 0xc0
	v_lshlrev_b32_e32 v0, 4, v0
	s_lshl_b32 s80, s37, 10
	s_min_u32 s5, s46, s18
	v_and_b32_e32 v0, 0x70, v0
	v_lshrrev_b32_e32 v21, 2, v16
	v_lshrrev_b32_e32 v20, 4, v16
	s_add_i32 s80, s80, 0
	s_ashr_i32 s4, s4, 6
	s_lshr_b32 s83, s5, 6
	v_lshl_add_u64 v[14:15], v[22:23], 0, v[0:1]
	v_xor_b32_e32 v0, v21, v20
	s_cmp_gt_u32 s82, 1
	v_lshlrev_b32_e32 v19, 3, v16
	v_lshlrev_b32_e32 v0, 6, v0
	s_cselect_b32 s68, s4, 0
	v_and_b32_e32 v19, 24, v19
	v_and_b32_e32 v0, 64, v0
	s_ashr_i32 s69, s68, 31
	v_lshl_add_u64 v[22:23], v[22:23], 0, v[0:1]
	v_lshlrev_b32_e32 v0, 1, v19
	s_lshl_b64 s[4:5], s[68:69], 16
	v_lshl_add_u64 v[120:121], v[22:23], 0, v[0:1]
	v_lshl_add_u64 v[22:23], v[14:15], 0, s[4:5]
	s_mov_b32 s18, m0
	s_mov_b32 m0, s80
	s_nop 0
	global_load_lds_dwordx4 v[22:23], off
	s_mov_b32 m0, s18
	s_sub_i32 s79, s83, s68
	s_add_i32 s18, s80, 0x4000
	v_lshl_add_u64 v[22:23], v[120:121], 0, s[4:5]
	s_add_u32 s4, s4, 0x10000
	v_lshl_add_u64 v[22:23], v[22:23], 0, s[8:9]
	s_addc_u32 s5, s5, 0
	s_mov_b32 s19, m0
	s_mov_b32 m0, s18
	s_nop 0
	global_load_lds_dwordx4 v[22:23], off
	s_mov_b32 m0, s19
	v_lshl_add_u64 v[22:23], v[14:15], 0, s[4:5]
	s_add_i32 s18, s80, 0x8000
	s_mov_b32 s19, m0
	s_mov_b32 m0, s18
	s_nop 0
	global_load_lds_dwordx4 v[22:23], off
	s_mov_b32 m0, s19
	v_lshl_add_u64 v[22:23], v[120:121], 0, s[4:5]
	s_add_i32 s4, s80, 0xc000
	v_lshl_add_u64 v[22:23], v[22:23], 0, s[8:9]
	s_mov_b32 s5, m0
	s_mov_b32 m0, s4
	s_nop 0
	global_load_lds_dwordx4 v[22:23], off
	s_mov_b32 m0, s5
	s_and_b32 s4, s81, 0xffffff00
	s_waitcnt vmcnt(2) lgkmcnt(0)
	s_barrier
	s_cmpk_eq_i32 s4, 0x100
	s_cselect_b64 s[70:71], -1, 0
	s_and_b64 vcc, exec, s[70:71]
	s_cbranch_vccz .LBB0_160
	s_cmp_lt_i32 s79, 3
	s_cbranch_scc1 .LBB0_159
	s_add_i32 s4, s68, 2
	s_mov_b32 s5, s36
	s_lshl_b64 s[4:5], s[4:5], 16
	v_lshl_add_u64 v[22:23], v[14:15], 0, s[4:5]
	s_add_i32 s18, s80, 0x10000
	s_mov_b32 s19, m0
	s_mov_b32 m0, s18
	s_nop 0
	global_load_lds_dwordx4 v[22:23], off
	s_mov_b32 m0, s19
	v_lshl_add_u64 v[22:23], v[120:121], 0, s[4:5]
	v_lshl_add_u64 v[22:23], v[22:23], 0, s[8:9]
	s_add_i32 s4, s80, 0x14000
	s_mov_b32 s5, m0
	s_mov_b32 m0, s4
	s_nop 0
	global_load_lds_dwordx4 v[22:23], off
	s_mov_b32 m0, s5
